# FNet stage-1 epilogue: pairs of 8-byte scattered stores merged into one 16-byte store via v_permlane16_swap (half the store instructions, 64 contiguous bytes per row)
# speedup vs baseline: 1.0119x; 1.0119x over previous
.LBB0_88:
	s_ashr_i32 s36, s35, 6
	s_ashr_i32 s37, s36, 31
	s_ashr_i32 s31, s30, 31
	s_lshl_b64 s[36:37], s[36:37], 18
	s_lshl_b64 s[44:45], s[30:31], 17
	v_readlane_b32 s46, v254, 55
	v_readlane_b32 s47, v254, 56
	s_add_u32 s20, s46, s36
	s_addc_u32 s31, s47, s37
	s_add_u32 s44, s20, s44
	s_addc_u32 s45, s31, s45
	s_and_b64 s[36:37], s[40:41], exec
	s_cselect_b32 s41, s45, s15
	s_cselect_b32 s40, s44, s14
	s_add_i32 s20, 16, 0x10000
	v_add_u32_e32 v35, s20, v33
	ds_read_b128 v[0:3], v35
	ds_read_b128 v[4:7], v35 offset:1024
	ds_read_b128 v[8:11], v35 offset:2048
	ds_read_b128 v[12:15], v35 offset:3072
	s_add_u32 s36, s14, 0x10080
	s_addc_u32 s37, s15, 0
	s_add_i32 s46, s4, 0xc000
	v_lshl_add_u64 v[60:61], s[36:37], 0, v[28:29]
	s_mov_b32 m0, s46
	s_add_i32 s31, s4, 0xe000
	ds_read_b128 v[16:19], v34
	ds_read_b128 v[20:23], v34 offset:1024
	ds_read_b128 v[36:39], v34 offset:2048
	ds_read_b128 v[40:43], v34 offset:3072
	ds_read_b128 v[44:47], v34 offset:4096
	ds_read_b128 v[48:51], v34 offset:5120
	ds_read_b128 v[52:55], v34 offset:6144
	ds_read_b128 v[56:59], v34 offset:7168
	global_load_lds_dwordx4 v[60:61], off
	v_lshl_add_u64 v[60:61], s[36:37], 0, v[26:27]
	s_mov_b32 m0, s31
	s_nop 0
	global_load_lds_dwordx4 v[60:61], off
	s_waitcnt lgkmcnt(8)
	s_barrier
	s_waitcnt lgkmcnt(0)
	s_setprio 1
	s_waitcnt lgkmcnt(0)
	v_mfma_f32_16x16x32_bf16 v[60:63], v[0:3], v[16:19], 0
	v_mfma_f32_16x16x32_bf16 v[64:67], v[8:11], v[16:19], 0
	v_mfma_f32_16x16x32_bf16 v[68:71], v[0:3], v[36:39], 0
	v_mfma_f32_16x16x32_bf16 v[72:75], v[8:11], v[36:39], 0
	v_mfma_f32_16x16x32_bf16 v[76:79], v[0:3], v[44:47], 0
	v_mfma_f32_16x16x32_bf16 v[80:83], v[8:11], v[44:47], 0
	v_mfma_f32_16x16x32_bf16 v[84:87], v[0:3], v[52:55], 0
	v_mfma_f32_16x16x32_bf16 v[88:91], v[8:11], v[52:55], 0
	v_mfma_f32_16x16x32_bf16 v[60:63], v[4:7], v[20:23], v[60:63]
	v_mfma_f32_16x16x32_bf16 v[64:67], v[12:15], v[20:23], v[64:67]
	v_mfma_f32_16x16x32_bf16 v[68:71], v[4:7], v[40:43], v[68:71]
	v_mfma_f32_16x16x32_bf16 v[72:75], v[12:15], v[40:43], v[72:75]
	v_mfma_f32_16x16x32_bf16 v[76:79], v[4:7], v[48:51], v[76:79]
	v_mfma_f32_16x16x32_bf16 v[80:83], v[12:15], v[48:51], v[80:83]
	v_mfma_f32_16x16x32_bf16 v[84:87], v[4:7], v[56:59], v[84:87]
	v_mfma_f32_16x16x32_bf16 v[88:91], v[12:15], v[56:59], v[88:91]
	s_setprio 0
	s_barrier
	s_add_i32 s37, 16, 0x14000
	v_lshl_add_u64 v[130:131], s[18:19], 0, v[128:129]
	s_mov_b64 s[48:49], 0x100
	s_add_i32 s36, s20, s1
	v_add_u32_e32 v138, s37, v33
	v_lshl_add_u64 v[108:109], v[130:131], 0, s[48:49]
	s_mov_b32 m0, s36
	v_lshl_add_u64 v[132:133], s[18:19], 0, v[24:25]
	s_add_i32 s18, s36, 0x2000
	ds_read_b128 v[92:95], v138
	ds_read_b128 v[96:99], v138 offset:1024
	ds_read_b128 v[100:103], v138 offset:2048
	ds_read_b128 v[104:107], v138 offset:3072
	global_load_lds_dwordx4 v[108:109], off
	v_lshl_add_u64 v[108:109], v[132:133], 0, s[48:49]
	s_mov_b32 m0, s18
	s_nop 0
	global_load_lds_dwordx4 v[108:109], off
	s_barrier
	s_waitcnt lgkmcnt(0)
	s_setprio 1
	s_waitcnt lgkmcnt(0)
	v_mfma_f32_16x16x32_bf16 v[108:111], v[92:95], v[16:19], 0
	v_mfma_f32_16x16x32_bf16 v[16:19], v[100:103], v[16:19], 0
	v_mfma_f32_16x16x32_bf16 v[108:111], v[96:99], v[20:23], v[108:111]
	v_mfma_f32_16x16x32_bf16 v[16:19], v[104:107], v[20:23], v[16:19]
	v_mfma_f32_16x16x32_bf16 v[20:23], v[92:95], v[36:39], 0
	v_mfma_f32_16x16x32_bf16 v[36:39], v[100:103], v[36:39], 0
	v_mfma_f32_16x16x32_bf16 v[20:23], v[96:99], v[40:43], v[20:23]
	v_mfma_f32_16x16x32_bf16 v[36:39], v[104:107], v[40:43], v[36:39]
	v_mfma_f32_16x16x32_bf16 v[40:43], v[92:95], v[44:47], 0
	v_mfma_f32_16x16x32_bf16 v[44:47], v[100:103], v[44:47], 0
	v_mfma_f32_16x16x32_bf16 v[40:43], v[96:99], v[48:51], v[40:43]
	v_mfma_f32_16x16x32_bf16 v[44:47], v[104:107], v[48:51], v[44:47]
	v_mfma_f32_16x16x32_bf16 v[48:51], v[92:95], v[52:55], 0
	v_mfma_f32_16x16x32_bf16 v[52:55], v[100:103], v[52:55], 0
	v_mfma_f32_16x16x32_bf16 v[48:51], v[96:99], v[56:59], v[48:51]
	v_mfma_f32_16x16x32_bf16 v[52:55], v[104:107], v[56:59], v[52:55]
	s_setprio 0
	v_lshl_add_u64 v[134:135], s[14:15], 0, v[28:29]
	s_mov_b32 m0, s4
	v_lshl_add_u64 v[136:137], v[134:135], 0, s[48:49]
	s_barrier
	ds_read_b128 v[56:59], v34 offset:16384
	ds_read_b128 v[112:115], v34 offset:17408
	ds_read_b128 v[116:119], v34 offset:18432
	ds_read_b128 v[120:123], v34 offset:19456
	ds_read_b128 v[124:127], v34 offset:20480
	ds_read_b128 v[144:147], v34 offset:21504
	ds_read_b128 v[148:151], v34 offset:22528
	ds_read_b128 v[152:155], v34 offset:23552
	global_load_lds_dwordx4 v[136:137], off
	v_lshl_add_u64 v[136:137], s[14:15], 0, v[26:27]
	v_lshl_add_u64 v[156:157], v[136:137], 0, s[48:49]
	s_mov_b32 m0, s5
	s_nop 0
	global_load_lds_dwordx4 v[156:157], off
	s_barrier
	s_waitcnt lgkmcnt(0)
	s_setprio 1
	s_waitcnt lgkmcnt(0)
	v_mfma_f32_16x16x32_bf16 v[156:159], v[0:3], v[56:59], 0
	v_mfma_f32_16x16x32_bf16 v[164:167], v[0:3], v[116:119], 0
	v_mfma_f32_16x16x32_bf16 v[172:175], v[0:3], v[124:127], 0
	v_mfma_f32_16x16x32_bf16 v[0:3], v[0:3], v[148:151], 0
	v_mfma_f32_16x16x32_bf16 v[156:159], v[4:7], v[112:115], v[156:159]
	v_mfma_f32_16x16x32_bf16 v[160:163], v[8:11], v[56:59], 0
	v_mfma_f32_16x16x32_bf16 v[164:167], v[4:7], v[120:123], v[164:167]
	v_mfma_f32_16x16x32_bf16 v[168:171], v[8:11], v[116:119], 0
	v_mfma_f32_16x16x32_bf16 v[172:175], v[4:7], v[144:147], v[172:175]
	v_mfma_f32_16x16x32_bf16 v[176:179], v[8:11], v[124:127], 0
	v_mfma_f32_16x16x32_bf16 v[0:3], v[4:7], v[152:155], v[0:3]
	v_mfma_f32_16x16x32_bf16 v[4:7], v[8:11], v[148:151], 0
	v_mfma_f32_16x16x32_bf16 v[160:163], v[12:15], v[112:115], v[160:163]
	v_mfma_f32_16x16x32_bf16 v[168:171], v[12:15], v[120:123], v[168:171]
	v_mfma_f32_16x16x32_bf16 v[176:179], v[12:15], v[144:147], v[176:179]
	v_mfma_f32_16x16x32_bf16 v[4:7], v[12:15], v[152:155], v[4:7]
	s_setprio 0
	s_barrier
	s_mov_b64 s[48:49], 0x900
	s_add_i32 s20, s37, s1
	v_lshl_add_u64 v[8:9], v[130:131], 0, s[48:49]
	s_mov_b32 m0, s20
	s_add_i32 s19, s20, 0x2000
	global_load_lds_dwordx4 v[8:9], off
	v_lshl_add_u64 v[8:9], v[132:133], 0, s[48:49]
	s_mov_b32 m0, s19
	s_nop 0
	global_load_lds_dwordx4 v[8:9], off
	s_waitcnt vmcnt(6)
	s_barrier
	s_setprio 1
	v_mfma_f32_16x16x32_bf16 v[8:11], v[92:95], v[56:59], 0
	v_mfma_f32_16x16x32_bf16 v[12:15], v[100:103], v[56:59], 0
	v_mfma_f32_16x16x32_bf16 v[8:11], v[96:99], v[112:115], v[8:11]
	v_mfma_f32_16x16x32_bf16 v[12:15], v[104:107], v[112:115], v[12:15]
	v_mfma_f32_16x16x32_bf16 v[56:59], v[92:95], v[116:119], 0
	v_mfma_f32_16x16x32_bf16 v[112:115], v[100:103], v[116:119], 0
	v_mfma_f32_16x16x32_bf16 v[116:119], v[92:95], v[124:127], 0
	v_mfma_f32_16x16x32_bf16 v[92:95], v[92:95], v[148:151], 0
	v_mfma_f32_16x16x32_bf16 v[56:59], v[96:99], v[120:123], v[56:59]
	v_mfma_f32_16x16x32_bf16 v[112:115], v[104:107], v[120:123], v[112:115]
	v_mfma_f32_16x16x32_bf16 v[116:119], v[96:99], v[144:147], v[116:119]
	v_mfma_f32_16x16x32_bf16 v[120:123], v[100:103], v[124:127], 0
	v_mfma_f32_16x16x32_bf16 v[92:95], v[96:99], v[152:155], v[92:95]
	v_mfma_f32_16x16x32_bf16 v[96:99], v[100:103], v[148:151], 0
	v_mfma_f32_16x16x32_bf16 v[120:123], v[104:107], v[144:147], v[120:123]
	v_mfma_f32_16x16x32_bf16 v[96:99], v[104:107], v[152:155], v[96:99]
	s_setprio 0
	s_add_i32 s37, 16, 0x18000
	v_add_u32_e32 v139, s37, v33
	s_barrier
	ds_read_b128 v[100:103], v139
	ds_read_b128 v[104:107], v139 offset:1024
	ds_read_b128 v[124:127], v139 offset:2048
	ds_read_b128 v[144:147], v139 offset:3072
	s_add_u32 s48, s14, 0x10100
	s_addc_u32 s49, s15, 0
	s_mov_b32 m0, s16
	v_lshl_add_u64 v[204:205], s[48:49], 0, v[28:29]
	ds_read_b128 v[148:151], v34 offset:32768
	ds_read_b128 v[152:155], v34 offset:33792
	ds_read_b128 v[180:183], v34 offset:34816
	ds_read_b128 v[184:187], v34 offset:35840
	ds_read_b128 v[188:191], v34 offset:36864
	ds_read_b128 v[192:195], v34 offset:37888
	ds_read_b128 v[196:199], v34 offset:38912
	ds_read_b128 v[200:203], v34 offset:39936
	global_load_lds_dwordx4 v[204:205], off
	v_lshl_add_u64 v[204:205], s[48:49], 0, v[26:27]
	s_mov_b32 m0, s17
	s_nop 0
	global_load_lds_dwordx4 v[204:205], off
	s_waitcnt lgkmcnt(8)
	s_barrier
	s_waitcnt lgkmcnt(0)
	s_setprio 1
	s_waitcnt lgkmcnt(0)
	v_mfma_f32_16x16x32_bf16 v[60:63], v[100:103], v[148:151], v[60:63]
	v_mfma_f32_16x16x32_bf16 v[64:67], v[124:127], v[148:151], v[64:67]
	v_mfma_f32_16x16x32_bf16 v[68:71], v[100:103], v[180:183], v[68:71]
	v_mfma_f32_16x16x32_bf16 v[72:75], v[124:127], v[180:183], v[72:75]
	v_mfma_f32_16x16x32_bf16 v[76:79], v[100:103], v[188:191], v[76:79]
	v_mfma_f32_16x16x32_bf16 v[80:83], v[124:127], v[188:191], v[80:83]
	v_mfma_f32_16x16x32_bf16 v[84:87], v[100:103], v[196:199], v[84:87]
	v_mfma_f32_16x16x32_bf16 v[88:91], v[124:127], v[196:199], v[88:91]
	v_mfma_f32_16x16x32_bf16 v[60:63], v[104:107], v[152:155], v[60:63]
	v_mfma_f32_16x16x32_bf16 v[64:67], v[144:147], v[152:155], v[64:67]
	v_mfma_f32_16x16x32_bf16 v[68:71], v[104:107], v[184:187], v[68:71]
	v_mfma_f32_16x16x32_bf16 v[72:75], v[144:147], v[184:187], v[72:75]
	v_mfma_f32_16x16x32_bf16 v[76:79], v[104:107], v[192:195], v[76:79]
	v_mfma_f32_16x16x32_bf16 v[80:83], v[144:147], v[192:195], v[80:83]
	v_mfma_f32_16x16x32_bf16 v[84:87], v[104:107], v[200:203], v[84:87]
	v_mfma_f32_16x16x32_bf16 v[88:91], v[144:147], v[200:203], v[88:91]
	s_setprio 0
	s_barrier
	s_add_i32 s48, 16, 0x1c000
	s_mov_b64 s[50:51], 0x180
	s_add_i32 s49, s37, s1
	v_add_u32_e32 v140, s48, v33
	v_lshl_add_u64 v[220:221], v[130:131], 0, s[50:51]
	s_mov_b32 m0, s49
	s_add_i32 s37, s49, 0x2000
	ds_read_b128 v[204:207], v140
	ds_read_b128 v[208:211], v140 offset:1024
	ds_read_b128 v[212:215], v140 offset:2048
	ds_read_b128 v[216:219], v140 offset:3072
	global_load_lds_dwordx4 v[220:221], off
	v_lshl_add_u64 v[220:221], v[132:133], 0, s[50:51]
	s_mov_b32 m0, s37
	s_nop 0
	global_load_lds_dwordx4 v[220:221], off
	s_barrier
	s_waitcnt lgkmcnt(0)
	s_setprio 1
	s_waitcnt lgkmcnt(0)
	v_mfma_f32_16x16x32_bf16 v[108:111], v[204:207], v[148:151], v[108:111]
	v_mfma_f32_16x16x32_bf16 v[16:19], v[212:215], v[148:151], v[16:19]
	v_mfma_f32_16x16x32_bf16 v[20:23], v[204:207], v[180:183], v[20:23]
	v_mfma_f32_16x16x32_bf16 v[36:39], v[212:215], v[180:183], v[36:39]
	v_mfma_f32_16x16x32_bf16 v[40:43], v[204:207], v[188:191], v[40:43]
	v_mfma_f32_16x16x32_bf16 v[44:47], v[212:215], v[188:191], v[44:47]
	v_mfma_f32_16x16x32_bf16 v[48:51], v[204:207], v[196:199], v[48:51]
	v_mfma_f32_16x16x32_bf16 v[52:55], v[212:215], v[196:199], v[52:55]
	v_mfma_f32_16x16x32_bf16 v[108:111], v[208:211], v[152:155], v[108:111]
	v_mfma_f32_16x16x32_bf16 v[16:19], v[216:219], v[152:155], v[16:19]
	v_mfma_f32_16x16x32_bf16 v[20:23], v[208:211], v[184:187], v[20:23]
	v_mfma_f32_16x16x32_bf16 v[36:39], v[216:219], v[184:187], v[36:39]
	v_mfma_f32_16x16x32_bf16 v[40:43], v[208:211], v[192:195], v[40:43]
	v_mfma_f32_16x16x32_bf16 v[44:47], v[216:219], v[192:195], v[44:47]
	v_mfma_f32_16x16x32_bf16 v[48:51], v[208:211], v[200:203], v[48:51]
	v_mfma_f32_16x16x32_bf16 v[52:55], v[216:219], v[200:203], v[52:55]
	s_setprio 0
	s_mov_b32 m0, s24
	v_lshl_add_u64 v[134:135], v[134:135], 0, s[50:51]
	s_barrier
	ds_read_b128 v[148:151], v34 offset:49152
	ds_read_b128 v[152:155], v34 offset:50176
	ds_read_b128 v[180:183], v34 offset:51200
	ds_read_b128 v[184:187], v34 offset:52224
	ds_read_b128 v[188:191], v34 offset:53248
	ds_read_b128 v[192:195], v34 offset:54272
	ds_read_b128 v[196:199], v34 offset:55296
	ds_read_b128 v[200:203], v34 offset:56320
	global_load_lds_dwordx4 v[134:135], off
	v_lshl_add_u64 v[134:135], v[136:137], 0, s[50:51]
	s_mov_b32 m0, s25
	s_nop 0
	global_load_lds_dwordx4 v[134:135], off
	s_barrier
	s_waitcnt lgkmcnt(0)
	s_setprio 1
	s_waitcnt lgkmcnt(0)
	v_mfma_f32_16x16x32_bf16 v[156:159], v[100:103], v[148:151], v[156:159]
	v_mfma_f32_16x16x32_bf16 v[160:163], v[124:127], v[148:151], v[160:163]
	v_mfma_f32_16x16x32_bf16 v[164:167], v[100:103], v[180:183], v[164:167]
	v_mfma_f32_16x16x32_bf16 v[168:171], v[124:127], v[180:183], v[168:171]
	v_mfma_f32_16x16x32_bf16 v[172:175], v[100:103], v[188:191], v[172:175]
	v_mfma_f32_16x16x32_bf16 v[176:179], v[124:127], v[188:191], v[176:179]
	v_mfma_f32_16x16x32_bf16 v[0:3], v[100:103], v[196:199], v[0:3]
	v_mfma_f32_16x16x32_bf16 v[4:7], v[124:127], v[196:199], v[4:7]
	v_mfma_f32_16x16x32_bf16 v[156:159], v[104:107], v[152:155], v[156:159]
	v_mfma_f32_16x16x32_bf16 v[160:163], v[144:147], v[152:155], v[160:163]
	v_mfma_f32_16x16x32_bf16 v[164:167], v[104:107], v[184:187], v[164:167]
	v_mfma_f32_16x16x32_bf16 v[168:171], v[144:147], v[184:187], v[168:171]
	v_mfma_f32_16x16x32_bf16 v[172:175], v[104:107], v[192:195], v[172:175]
	v_mfma_f32_16x16x32_bf16 v[176:179], v[144:147], v[192:195], v[176:179]
	v_mfma_f32_16x16x32_bf16 v[0:3], v[104:107], v[200:203], v[0:3]
	v_mfma_f32_16x16x32_bf16 v[4:7], v[144:147], v[200:203], v[4:7]
	s_setprio 0
	s_barrier
	s_mov_b64 s[50:51], 0x980
	s_add_i32 s48, s48, s1
	v_lshl_add_u64 v[100:101], v[130:131], 0, s[50:51]
	s_mov_b32 m0, s48
	s_add_i32 s47, s48, 0x2000
	global_load_lds_dwordx4 v[100:101], off
	v_lshl_add_u64 v[100:101], v[132:133], 0, s[50:51]
	s_mov_b32 m0, s47
	s_nop 0
	global_load_lds_dwordx4 v[100:101], off
	s_waitcnt vmcnt(6)
	s_barrier
	s_setprio 1
	v_mfma_f32_16x16x32_bf16 v[8:11], v[204:207], v[148:151], v[8:11]
	v_mfma_f32_16x16x32_bf16 v[12:15], v[212:215], v[148:151], v[12:15]
	v_mfma_f32_16x16x32_bf16 v[56:59], v[204:207], v[180:183], v[56:59]
	v_mfma_f32_16x16x32_bf16 v[100:103], v[212:215], v[180:183], v[112:115]
	v_mfma_f32_16x16x32_bf16 v[104:107], v[204:207], v[188:191], v[116:119]
	v_mfma_f32_16x16x32_bf16 v[112:115], v[212:215], v[188:191], v[120:123]
	v_mfma_f32_16x16x32_bf16 v[92:95], v[204:207], v[196:199], v[92:95]
	v_mfma_f32_16x16x32_bf16 v[96:99], v[212:215], v[196:199], v[96:99]
	v_mfma_f32_16x16x32_bf16 v[8:11], v[208:211], v[152:155], v[8:11]
	v_mfma_f32_16x16x32_bf16 v[12:15], v[216:219], v[152:155], v[12:15]
	v_mfma_f32_16x16x32_bf16 v[56:59], v[208:211], v[184:187], v[56:59]
	v_mfma_f32_16x16x32_bf16 v[100:103], v[216:219], v[184:187], v[100:103]
	v_mfma_f32_16x16x32_bf16 v[104:107], v[208:211], v[192:195], v[104:107]
	v_mfma_f32_16x16x32_bf16 v[112:115], v[216:219], v[192:195], v[112:115]
	v_mfma_f32_16x16x32_bf16 v[92:95], v[208:211], v[200:203], v[92:95]
	v_mfma_f32_16x16x32_bf16 v[96:99], v[216:219], v[200:203], v[96:99]
	s_setprio 0
	s_barrier
	ds_read_b128 v[116:119], v35
	ds_read_b128 v[120:123], v35 offset:1024
	ds_read_b128 v[124:127], v35 offset:2048
	ds_read_b128 v[144:147], v35 offset:3072
	s_add_u32 s14, s14, 0x10180
	s_addc_u32 s15, s15, 0
	s_mov_b32 m0, s46
	v_lshl_add_u64 v[130:131], s[14:15], 0, v[28:29]
	ds_read_b128 v[148:151], v34
	ds_read_b128 v[152:155], v34 offset:1024
	ds_read_b128 v[180:183], v34 offset:2048
	ds_read_b128 v[184:187], v34 offset:3072
	ds_read_b128 v[188:191], v34 offset:4096
	ds_read_b128 v[192:195], v34 offset:5120
	ds_read_b128 v[196:199], v34 offset:6144
	ds_read_b128 v[200:203], v34 offset:7168
	global_load_lds_dwordx4 v[130:131], off
	v_lshl_add_u64 v[130:131], s[14:15], 0, v[26:27]
	s_mov_b32 m0, s31
	s_nop 0
	global_load_lds_dwordx4 v[130:131], off
	s_waitcnt lgkmcnt(8)
	s_barrier
	s_waitcnt lgkmcnt(0)
	s_setprio 1
	s_waitcnt lgkmcnt(0)
	v_mfma_f32_16x16x32_bf16 v[60:63], v[116:119], v[148:151], v[60:63]
	v_mfma_f32_16x16x32_bf16 v[64:67], v[124:127], v[148:151], v[64:67]
	v_mfma_f32_16x16x32_bf16 v[68:71], v[116:119], v[180:183], v[68:71]
	v_mfma_f32_16x16x32_bf16 v[72:75], v[124:127], v[180:183], v[72:75]
	v_mfma_f32_16x16x32_bf16 v[76:79], v[116:119], v[188:191], v[76:79]
	v_mfma_f32_16x16x32_bf16 v[80:83], v[124:127], v[188:191], v[80:83]
	v_mfma_f32_16x16x32_bf16 v[84:87], v[116:119], v[196:199], v[84:87]
	v_mfma_f32_16x16x32_bf16 v[88:91], v[124:127], v[196:199], v[88:91]
	v_mfma_f32_16x16x32_bf16 v[60:63], v[120:123], v[152:155], v[60:63]
	v_mfma_f32_16x16x32_bf16 v[64:67], v[144:147], v[152:155], v[64:67]
	v_mfma_f32_16x16x32_bf16 v[68:71], v[120:123], v[184:187], v[68:71]
	v_mfma_f32_16x16x32_bf16 v[72:75], v[144:147], v[184:187], v[72:75]
	v_mfma_f32_16x16x32_bf16 v[76:79], v[120:123], v[192:195], v[76:79]
	v_mfma_f32_16x16x32_bf16 v[80:83], v[144:147], v[192:195], v[80:83]
	v_mfma_f32_16x16x32_bf16 v[84:87], v[120:123], v[200:203], v[84:87]
	v_mfma_f32_16x16x32_bf16 v[88:91], v[144:147], v[200:203], v[88:91]
	s_setprio 0
	s_barrier
	s_mov_b32 m0, s36
	v_lshl_add_u64 v[130:131], s[42:43], 0, v[128:129]
	ds_read_b128 v[204:207], v138
	ds_read_b128 v[208:211], v138 offset:1024
	ds_read_b128 v[212:215], v138 offset:2048
	ds_read_b128 v[216:219], v138 offset:3072
	global_load_lds_dwordx4 v[130:131], off
	v_lshl_add_u64 v[132:133], s[42:43], 0, v[24:25]
	s_mov_b32 m0, s18
	s_nop 0
	global_load_lds_dwordx4 v[132:133], off
	s_barrier
	s_waitcnt lgkmcnt(0)
	s_setprio 1
	s_waitcnt lgkmcnt(0)
	v_mfma_f32_16x16x32_bf16 v[108:111], v[204:207], v[148:151], v[108:111]
	v_mfma_f32_16x16x32_bf16 v[16:19], v[212:215], v[148:151], v[16:19]
	v_mfma_f32_16x16x32_bf16 v[20:23], v[204:207], v[180:183], v[20:23]
	v_mfma_f32_16x16x32_bf16 v[36:39], v[212:215], v[180:183], v[36:39]
	v_mfma_f32_16x16x32_bf16 v[40:43], v[204:207], v[188:191], v[40:43]
	v_mfma_f32_16x16x32_bf16 v[44:47], v[212:215], v[188:191], v[44:47]
	v_mfma_f32_16x16x32_bf16 v[48:51], v[204:207], v[196:199], v[48:51]
	v_mfma_f32_16x16x32_bf16 v[52:55], v[212:215], v[196:199], v[52:55]
	v_mfma_f32_16x16x32_bf16 v[108:111], v[208:211], v[152:155], v[108:111]
	v_mfma_f32_16x16x32_bf16 v[16:19], v[216:219], v[152:155], v[16:19]
	v_mfma_f32_16x16x32_bf16 v[20:23], v[208:211], v[184:187], v[20:23]
	v_mfma_f32_16x16x32_bf16 v[36:39], v[216:219], v[184:187], v[36:39]
	v_mfma_f32_16x16x32_bf16 v[40:43], v[208:211], v[192:195], v[40:43]
	v_mfma_f32_16x16x32_bf16 v[44:47], v[216:219], v[192:195], v[44:47]
	v_mfma_f32_16x16x32_bf16 v[48:51], v[208:211], v[200:203], v[48:51]
	v_mfma_f32_16x16x32_bf16 v[52:55], v[216:219], v[200:203], v[52:55]
	s_setprio 0
	s_mov_b32 m0, s4
	v_lshl_add_u64 v[134:135], s[40:41], 0, v[28:29]
	s_barrier
	ds_read_b128 v[148:151], v34 offset:16384
	ds_read_b128 v[152:155], v34 offset:17408
	ds_read_b128 v[180:183], v34 offset:18432
	ds_read_b128 v[184:187], v34 offset:19456
	ds_read_b128 v[188:191], v34 offset:20480
	ds_read_b128 v[192:195], v34 offset:21504
	ds_read_b128 v[196:199], v34 offset:22528
	ds_read_b128 v[200:203], v34 offset:23552
	global_load_lds_dwordx4 v[134:135], off
	v_lshl_add_u64 v[136:137], s[40:41], 0, v[26:27]
	s_mov_b32 m0, s5
	s_nop 0
	global_load_lds_dwordx4 v[136:137], off
	s_barrier
	s_waitcnt lgkmcnt(0)
	s_setprio 1
	s_waitcnt lgkmcnt(0)
	v_mfma_f32_16x16x32_bf16 v[156:159], v[116:119], v[148:151], v[156:159]
	v_mfma_f32_16x16x32_bf16 v[160:163], v[124:127], v[148:151], v[160:163]
	v_mfma_f32_16x16x32_bf16 v[164:167], v[116:119], v[180:183], v[164:167]
	v_mfma_f32_16x16x32_bf16 v[168:171], v[124:127], v[180:183], v[168:171]
	v_mfma_f32_16x16x32_bf16 v[172:175], v[116:119], v[188:191], v[172:175]
	v_mfma_f32_16x16x32_bf16 v[176:179], v[124:127], v[188:191], v[176:179]
	v_mfma_f32_16x16x32_bf16 v[0:3], v[116:119], v[196:199], v[0:3]
	v_mfma_f32_16x16x32_bf16 v[4:7], v[124:127], v[196:199], v[4:7]
	v_mfma_f32_16x16x32_bf16 v[156:159], v[120:123], v[152:155], v[156:159]
	v_mfma_f32_16x16x32_bf16 v[160:163], v[144:147], v[152:155], v[160:163]
	v_mfma_f32_16x16x32_bf16 v[164:167], v[120:123], v[184:187], v[164:167]
	v_mfma_f32_16x16x32_bf16 v[168:171], v[144:147], v[184:187], v[168:171]
	v_mfma_f32_16x16x32_bf16 v[172:175], v[120:123], v[192:195], v[172:175]
	v_mfma_f32_16x16x32_bf16 v[176:179], v[144:147], v[192:195], v[176:179]
	v_mfma_f32_16x16x32_bf16 v[0:3], v[120:123], v[200:203], v[0:3]
	v_mfma_f32_16x16x32_bf16 v[116:119], v[144:147], v[200:203], v[4:7]
	s_setprio 0
	s_barrier
	s_mov_b64 s[14:15], 0x800
	s_mov_b32 m0, s20
	v_lshl_add_u64 v[4:5], v[130:131], 0, s[14:15]
	global_load_lds_dwordx4 v[4:5], off
	v_lshl_add_u64 v[4:5], v[132:133], 0, s[14:15]
	s_mov_b32 m0, s19
	s_nop 0
	global_load_lds_dwordx4 v[4:5], off
	s_waitcnt vmcnt(6)
	s_barrier
	s_setprio 1
	v_mfma_f32_16x16x32_bf16 v[4:7], v[204:207], v[148:151], v[8:11]
	v_mfma_f32_16x16x32_bf16 v[8:11], v[208:211], v[152:155], v[4:7]
	v_mfma_f32_16x16x32_bf16 v[4:7], v[212:215], v[148:151], v[12:15]
	v_mfma_f32_16x16x32_bf16 v[12:15], v[216:219], v[152:155], v[4:7]
	v_mfma_f32_16x16x32_bf16 v[4:7], v[204:207], v[180:183], v[56:59]
	v_mfma_f32_16x16x32_bf16 v[56:59], v[208:211], v[184:187], v[4:7]
	v_mfma_f32_16x16x32_bf16 v[4:7], v[212:215], v[180:183], v[100:103]
	v_mfma_f32_16x16x32_bf16 v[100:103], v[216:219], v[184:187], v[4:7]
	v_mfma_f32_16x16x32_bf16 v[4:7], v[204:207], v[188:191], v[104:107]
	v_mfma_f32_16x16x32_bf16 v[104:107], v[208:211], v[192:195], v[4:7]
	v_mfma_f32_16x16x32_bf16 v[4:7], v[212:215], v[188:191], v[112:115]
	v_mfma_f32_16x16x32_bf16 v[112:115], v[216:219], v[192:195], v[4:7]
	v_mfma_f32_16x16x32_bf16 v[4:7], v[204:207], v[196:199], v[92:95]
	v_mfma_f32_16x16x32_bf16 v[92:95], v[208:211], v[200:203], v[4:7]
	v_mfma_f32_16x16x32_bf16 v[4:7], v[212:215], v[196:199], v[96:99]
	v_mfma_f32_16x16x32_bf16 v[96:99], v[216:219], v[200:203], v[4:7]
	s_setprio 0
	s_barrier
	s_nop 4
	ds_read_b128 v[4:7], v139
	ds_read_b128 v[120:123], v139 offset:1024
	ds_read_b128 v[124:127], v139 offset:2048
	ds_read_b128 v[144:147], v139 offset:3072
	s_add_u32 s14, s40, 0x10000
	s_addc_u32 s15, s41, 0
	s_mov_b32 m0, s16
	v_lshl_add_u64 v[204:205], s[14:15], 0, v[28:29]
	ds_read_b128 v[148:151], v34 offset:32768
	ds_read_b128 v[152:155], v34 offset:33792
	ds_read_b128 v[180:183], v34 offset:34816
	ds_read_b128 v[184:187], v34 offset:35840
	ds_read_b128 v[188:191], v34 offset:36864
	ds_read_b128 v[192:195], v34 offset:37888
	ds_read_b128 v[196:199], v34 offset:38912
	ds_read_b128 v[200:203], v34 offset:39936
	global_load_lds_dwordx4 v[204:205], off
	v_lshl_add_u64 v[204:205], s[14:15], 0, v[26:27]
	s_mov_b32 m0, s17
	s_nop 0
	global_load_lds_dwordx4 v[204:205], off
	s_waitcnt lgkmcnt(8)
	s_barrier
	s_waitcnt lgkmcnt(0)
	s_setprio 1
	s_waitcnt lgkmcnt(0)
	v_mfma_f32_16x16x32_bf16 v[60:63], v[4:7], v[148:151], v[60:63]
	v_mfma_f32_16x16x32_bf16 v[64:67], v[124:127], v[148:151], v[64:67]
	v_mfma_f32_16x16x32_bf16 v[68:71], v[4:7], v[180:183], v[68:71]
	v_mfma_f32_16x16x32_bf16 v[72:75], v[124:127], v[180:183], v[72:75]
	v_mfma_f32_16x16x32_bf16 v[76:79], v[4:7], v[188:191], v[76:79]
	v_mfma_f32_16x16x32_bf16 v[80:83], v[124:127], v[188:191], v[80:83]
	v_mfma_f32_16x16x32_bf16 v[84:87], v[4:7], v[196:199], v[84:87]
	v_mfma_f32_16x16x32_bf16 v[88:91], v[124:127], v[196:199], v[88:91]
	v_mfma_f32_16x16x32_bf16 v[60:63], v[120:123], v[152:155], v[60:63]
	v_mfma_f32_16x16x32_bf16 v[64:67], v[144:147], v[152:155], v[64:67]
	v_mfma_f32_16x16x32_bf16 v[68:71], v[120:123], v[184:187], v[68:71]
	v_mfma_f32_16x16x32_bf16 v[72:75], v[144:147], v[184:187], v[72:75]
	v_mfma_f32_16x16x32_bf16 v[76:79], v[120:123], v[192:195], v[76:79]
	v_mfma_f32_16x16x32_bf16 v[80:83], v[144:147], v[192:195], v[80:83]
	v_mfma_f32_16x16x32_bf16 v[84:87], v[120:123], v[200:203], v[84:87]
	v_mfma_f32_16x16x32_bf16 v[88:91], v[144:147], v[200:203], v[88:91]
	s_setprio 0
	s_barrier
	s_mov_b32 m0, s49
	v_lshl_add_u64 v[220:221], v[130:131], 0, s[28:29]
	ds_read_b128 v[204:207], v140
	ds_read_b128 v[208:211], v140 offset:1024
	ds_read_b128 v[212:215], v140 offset:2048
	ds_read_b128 v[216:219], v140 offset:3072
	global_load_lds_dwordx4 v[220:221], off
	v_lshl_add_u64 v[220:221], v[132:133], 0, s[28:29]
	s_mov_b32 m0, s37
	s_nop 0
	global_load_lds_dwordx4 v[220:221], off
	s_barrier
	s_waitcnt lgkmcnt(0)
	s_setprio 1
	s_waitcnt lgkmcnt(0)
	v_mfma_f32_16x16x32_bf16 v[16:19], v[212:215], v[148:151], v[16:19]
	v_mfma_f32_16x16x32_bf16 v[108:111], v[204:207], v[148:151], v[108:111]
	v_mfma_f32_16x16x32_bf16 v[148:151], v[216:219], v[152:155], v[16:19]
	v_mfma_f32_16x16x32_bf16 v[16:19], v[204:207], v[180:183], v[20:23]
	v_mfma_f32_16x16x32_bf16 v[108:111], v[208:211], v[152:155], v[108:111]
	v_mfma_f32_16x16x32_bf16 v[152:155], v[208:211], v[184:187], v[16:19]
	v_mfma_f32_16x16x32_bf16 v[16:19], v[212:215], v[180:183], v[36:39]
	v_mfma_f32_16x16x32_bf16 v[36:39], v[216:219], v[184:187], v[16:19]
	v_mfma_f32_16x16x32_bf16 v[16:19], v[204:207], v[188:191], v[40:43]
	v_mfma_f32_16x16x32_bf16 v[40:43], v[208:211], v[192:195], v[16:19]
	v_mfma_f32_16x16x32_bf16 v[16:19], v[212:215], v[188:191], v[44:47]
	v_mfma_f32_16x16x32_bf16 v[44:47], v[216:219], v[192:195], v[16:19]
	v_mfma_f32_16x16x32_bf16 v[16:19], v[204:207], v[196:199], v[48:51]
	v_mfma_f32_16x16x32_bf16 v[48:51], v[208:211], v[200:203], v[16:19]
	v_mfma_f32_16x16x32_bf16 v[16:19], v[212:215], v[196:199], v[52:55]
	v_mfma_f32_16x16x32_bf16 v[52:55], v[216:219], v[200:203], v[16:19]
	s_setprio 0
	s_mov_b32 m0, s24
	s_nop 4
	v_lshl_add_u64 v[16:17], v[134:135], 0, s[28:29]
	s_barrier
	ds_read_b128 v[180:183], v34 offset:49152
	ds_read_b128 v[184:187], v34 offset:50176
	ds_read_b128 v[188:191], v34 offset:51200
	ds_read_b128 v[192:195], v34 offset:52224
	ds_read_b128 v[196:199], v34 offset:53248
	ds_read_b128 v[200:203], v34 offset:54272
	ds_read_b128 v[220:223], v34 offset:55296
	ds_read_b128 v[224:227], v34 offset:56320
	global_load_lds_dwordx4 v[16:17], off
	v_lshl_add_u64 v[16:17], v[136:137], 0, s[28:29]
	s_mov_b32 m0, s25
	s_nop 0
	global_load_lds_dwordx4 v[16:17], off
	s_barrier
	s_waitcnt lgkmcnt(0)
	s_setprio 1
	s_waitcnt lgkmcnt(0)
	v_mfma_f32_16x16x32_bf16 v[16:19], v[4:7], v[180:183], v[156:159]
	v_mfma_f32_16x16x32_bf16 v[156:159], v[120:123], v[184:187], v[16:19]
	v_mfma_f32_16x16x32_bf16 v[16:19], v[124:127], v[180:183], v[160:163]
	v_mfma_f32_16x16x32_bf16 v[160:163], v[144:147], v[184:187], v[16:19]
	v_mfma_f32_16x16x32_bf16 v[16:19], v[4:7], v[188:191], v[164:167]
	v_mfma_f32_16x16x32_bf16 v[164:167], v[120:123], v[192:195], v[16:19]
	v_mfma_f32_16x16x32_bf16 v[16:19], v[124:127], v[188:191], v[168:171]
	v_mfma_f32_16x16x32_bf16 v[168:171], v[144:147], v[192:195], v[16:19]
	v_mfma_f32_16x16x32_bf16 v[16:19], v[4:7], v[196:199], v[172:175]
	v_mfma_f32_16x16x32_bf16 v[0:3], v[4:7], v[220:223], v[0:3]
	v_mfma_f32_16x16x32_bf16 v[20:23], v[120:123], v[200:203], v[16:19]
	v_mfma_f32_16x16x32_bf16 v[16:19], v[124:127], v[196:199], v[176:179]
	v_mfma_f32_16x16x32_bf16 v[4:7], v[120:123], v[224:227], v[0:3]
	v_mfma_f32_16x16x32_bf16 v[0:3], v[124:127], v[220:223], v[116:119]
	v_mfma_f32_16x16x32_bf16 v[16:19], v[144:147], v[200:203], v[16:19]
	v_mfma_f32_16x16x32_bf16 v[0:3], v[144:147], v[224:227], v[0:3]
	s_setprio 0
	s_barrier
	s_mov_b64 s[14:15], 0x880
	s_mov_b32 m0, s48
	v_lshl_add_u64 v[116:117], v[130:131], 0, s[14:15]
	global_load_lds_dwordx4 v[116:117], off
	v_lshl_add_u64 v[116:117], v[132:133], 0, s[14:15]
	s_mov_b32 m0, s47
	s_nop 0
	global_load_lds_dwordx4 v[116:117], off
	s_waitcnt vmcnt(6)
	s_barrier
	s_setprio 1
	v_mfma_f32_16x16x32_bf16 v[8:11], v[204:207], v[180:183], v[8:11]
	v_mfma_f32_16x16x32_bf16 v[116:119], v[208:211], v[184:187], v[8:11]
	v_mfma_f32_16x16x32_bf16 v[8:11], v[212:215], v[180:183], v[12:15]
	v_mfma_f32_16x16x32_bf16 v[120:123], v[216:219], v[184:187], v[8:11]
	v_mfma_f32_16x16x32_bf16 v[8:11], v[204:207], v[188:191], v[56:59]
	v_mfma_f32_16x16x32_bf16 v[56:59], v[208:211], v[192:195], v[8:11]
	v_mfma_f32_16x16x32_bf16 v[8:11], v[212:215], v[188:191], v[100:103]
	v_mfma_f32_16x16x32_bf16 v[100:103], v[216:219], v[192:195], v[8:11]
	v_mfma_f32_16x16x32_bf16 v[8:11], v[204:207], v[196:199], v[104:107]
	v_mfma_f32_16x16x32_bf16 v[104:107], v[208:211], v[200:203], v[8:11]
	v_mfma_f32_16x16x32_bf16 v[8:11], v[212:215], v[196:199], v[112:115]
	v_mfma_f32_16x16x32_bf16 v[112:115], v[216:219], v[200:203], v[8:11]
	v_mfma_f32_16x16x32_bf16 v[8:11], v[204:207], v[220:223], v[92:95]
	v_mfma_f32_16x16x32_bf16 v[12:15], v[208:211], v[224:227], v[8:11]
	v_mfma_f32_16x16x32_bf16 v[8:11], v[212:215], v[220:223], v[96:99]
	v_mfma_f32_16x16x32_bf16 v[8:11], v[216:219], v[224:227], v[8:11]
	v_mbcnt_lo_u32_b32 v228, -1, 0
	v_mbcnt_hi_u32_b32 v228, -1, v228
	v_and_b32_e32 v228, 16, v228
	v_lshrrev_b32_e32 v229, 1, v228
	v_add_u32_e32 v228, v228, v229
	v_mov_b32_e32 v229, 0
	s_setprio 0
	s_lshl_b32 s13, s13, 2
	s_and_b32 s14, s13, 0xffffff00
	v_add_u32_e32 v92, s14, v32
	v_ashrrev_i32_e32 v93, 31, v92
	s_and_b32 s92, s13, 0xfc
	s_ashr_i32 s13, s12, 31
	v_lshlrev_b64 v[94:95], 8, v[92:93]
	v_lshl_add_u64 v[94:95], v[94:95], 0, s[12:13]
	v_lshl_add_u64 v[96:97], v[94:95], 0, s[92:93]
	v_lshlrev_b64 v[96:97], 8, v[96:97]
	v_lshl_add_u64 v[96:97], v[30:31], 0, v[96:97]
	s_barrier
	v_cvt_pk_bf16_f32 v244, v60, v61
	v_cvt_pk_bf16_f32 v245, v62, v63
	v_cvt_pk_bf16_f32 v246, v64, v65
	v_cvt_pk_bf16_f32 v247, v66, v67
	v_lshl_add_u64 v[96:97], v[96:97], 0, v[228:229]
	s_nop 0
	v_permlane16_swap_b32_e32 v244, v246
	v_permlane16_swap_b32_e32 v245, v247
	global_store_dwordx4 v[96:97], v[244:247], off
	s_nop 1
	s_or_b32 s14, s92, 2
	s_mov_b32 s15, s93
	v_lshl_add_u64 v[60:61], v[94:95], 0, s[14:15]
	v_lshlrev_b64 v[60:61], 8, v[60:61]
	v_lshl_add_u64 v[60:61], v[30:31], 0, v[60:61]
	v_cvt_pk_bf16_f32 v244, v108, v109
	v_cvt_pk_bf16_f32 v245, v110, v111
	v_cvt_pk_bf16_f32 v246, v148, v149
	v_cvt_pk_bf16_f32 v247, v150, v151
	v_lshl_add_u64 v[60:61], v[60:61], 0, v[228:229]
	s_nop 0
	v_permlane16_swap_b32_e32 v244, v246
	v_permlane16_swap_b32_e32 v245, v247
	global_store_dwordx4 v[60:61], v[244:247], off
	s_nop 1
	v_or_b32_e32 v60, 16, v92
	v_ashrrev_i32_e32 v61, 31, v60
	v_lshlrev_b64 v[60:61], 8, v[60:61]
	v_lshl_add_u64 v[60:61], v[60:61], 0, s[12:13]
	v_lshl_add_u64 v[62:63], v[60:61], 0, s[92:93]
	v_lshl_add_u64 v[60:61], v[60:61], 0, s[14:15]
	v_lshlrev_b64 v[60:61], 8, v[60:61]
	v_lshl_add_u64 v[60:61], v[30:31], 0, v[60:61]
	v_cvt_pk_bf16_f32 v244, v152, v153
	v_cvt_pk_bf16_f32 v245, v154, v155
	v_cvt_pk_bf16_f32 v246, v36, v37
	v_cvt_pk_bf16_f32 v247, v38, v39
	v_lshl_add_u64 v[60:61], v[60:61], 0, v[228:229]
	s_nop 0
	v_permlane16_swap_b32_e32 v244, v246
	v_permlane16_swap_b32_e32 v245, v247
	global_store_dwordx4 v[60:61], v[244:247], off
	s_nop 1
	v_or_b32_e32 v36, 32, v92
	v_ashrrev_i32_e32 v37, 31, v36
	v_lshlrev_b64 v[62:63], 8, v[62:63]
	v_lshlrev_b64 v[36:37], 8, v[36:37]
	v_lshl_add_u64 v[62:63], v[30:31], 0, v[62:63]
	v_lshl_add_u64 v[36:37], v[36:37], 0, s[12:13]
	v_cvt_pk_bf16_f32 v244, v68, v69
	v_cvt_pk_bf16_f32 v245, v70, v71
	v_cvt_pk_bf16_f32 v246, v72, v73
	v_cvt_pk_bf16_f32 v247, v74, v75
	v_lshl_add_u64 v[62:63], v[62:63], 0, v[228:229]
	s_nop 0
	v_permlane16_swap_b32_e32 v244, v246
	v_permlane16_swap_b32_e32 v245, v247
	global_store_dwordx4 v[62:63], v[244:247], off
	s_nop 1
	v_lshl_add_u64 v[38:39], v[36:37], 0, s[92:93]
	v_lshlrev_b64 v[38:39], 8, v[38:39]
	v_lshl_add_u64 v[38:39], v[30:31], 0, v[38:39]
	v_lshl_add_u64 v[36:37], v[36:37], 0, s[14:15]
	v_cvt_pk_bf16_f32 v244, v76, v77
	v_cvt_pk_bf16_f32 v245, v78, v79
	v_cvt_pk_bf16_f32 v246, v80, v81
	v_cvt_pk_bf16_f32 v247, v82, v83
	v_lshl_add_u64 v[38:39], v[38:39], 0, v[228:229]
	s_nop 0
	v_permlane16_swap_b32_e32 v244, v246
	v_permlane16_swap_b32_e32 v245, v247
	global_store_dwordx4 v[38:39], v[244:247], off
	s_nop 1
	v_lshlrev_b64 v[36:37], 8, v[36:37]
	v_lshl_add_u64 v[36:37], v[30:31], 0, v[36:37]
	v_cvt_pk_bf16_f32 v244, v40, v41
	v_cvt_pk_bf16_f32 v245, v42, v43
	v_cvt_pk_bf16_f32 v246, v44, v45
	v_cvt_pk_bf16_f32 v247, v46, v47
	v_lshl_add_u64 v[36:37], v[36:37], 0, v[228:229]
	s_nop 0
	v_permlane16_swap_b32_e32 v244, v246
	v_permlane16_swap_b32_e32 v245, v247
	global_store_dwordx4 v[36:37], v[244:247], off
	s_nop 1
	v_or_b32_e32 v36, 48, v92
	v_ashrrev_i32_e32 v37, 31, v36
	v_lshlrev_b64 v[36:37], 8, v[36:37]
	v_lshl_add_u64 v[36:37], v[36:37], 0, s[12:13]
	v_lshl_add_u64 v[38:39], v[36:37], 0, s[92:93]
	v_lshlrev_b64 v[38:39], 8, v[38:39]
	v_lshl_add_u64 v[38:39], v[30:31], 0, v[38:39]
	v_lshl_add_u64 v[36:37], v[36:37], 0, s[14:15]
	v_cvt_pk_bf16_f32 v244, v84, v85
	v_cvt_pk_bf16_f32 v245, v86, v87
	v_cvt_pk_bf16_f32 v246, v88, v89
	v_cvt_pk_bf16_f32 v247, v90, v91
	v_lshl_add_u64 v[38:39], v[38:39], 0, v[228:229]
	s_nop 0
	v_permlane16_swap_b32_e32 v244, v246
	v_permlane16_swap_b32_e32 v245, v247
	global_store_dwordx4 v[38:39], v[244:247], off
	s_nop 1
	v_lshlrev_b64 v[36:37], 8, v[36:37]
	v_lshl_add_u64 v[36:37], v[30:31], 0, v[36:37]
	v_cvt_pk_bf16_f32 v244, v48, v49
	v_cvt_pk_bf16_f32 v245, v50, v51
	v_cvt_pk_bf16_f32 v246, v52, v53
	v_cvt_pk_bf16_f32 v247, v54, v55
	v_lshl_add_u64 v[36:37], v[36:37], 0, v[228:229]
	s_nop 0
	v_permlane16_swap_b32_e32 v244, v246
	v_permlane16_swap_b32_e32 v245, v247
	global_store_dwordx4 v[36:37], v[244:247], off
	s_nop 1
	v_add_u32_e32 v36, 0x80, v92
	v_ashrrev_i32_e32 v37, 31, v36
	v_lshlrev_b64 v[36:37], 8, v[36:37]
	v_lshl_add_u64 v[36:37], v[36:37], 0, s[12:13]
	v_lshl_add_u64 v[38:39], v[36:37], 0, s[92:93]
	v_lshlrev_b64 v[38:39], 8, v[38:39]
	v_lshl_add_u64 v[38:39], v[30:31], 0, v[38:39]
	v_lshl_add_u64 v[36:37], v[36:37], 0, s[14:15]
	v_cvt_pk_bf16_f32 v244, v156, v157
	v_cvt_pk_bf16_f32 v245, v158, v159
	v_cvt_pk_bf16_f32 v246, v160, v161
	v_cvt_pk_bf16_f32 v247, v162, v163
	v_lshl_add_u64 v[38:39], v[38:39], 0, v[228:229]
	s_nop 0
	v_permlane16_swap_b32_e32 v244, v246
	v_permlane16_swap_b32_e32 v245, v247
	global_store_dwordx4 v[38:39], v[244:247], off
	s_nop 1
	v_lshlrev_b64 v[36:37], 8, v[36:37]
	v_lshl_add_u64 v[36:37], v[30:31], 0, v[36:37]
	v_cvt_pk_bf16_f32 v244, v116, v117
	v_cvt_pk_bf16_f32 v245, v118, v119
	v_cvt_pk_bf16_f32 v246, v120, v121
	v_cvt_pk_bf16_f32 v247, v122, v123
	v_lshl_add_u64 v[36:37], v[36:37], 0, v[228:229]
	s_nop 0
	v_permlane16_swap_b32_e32 v244, v246
	v_permlane16_swap_b32_e32 v245, v247
	global_store_dwordx4 v[36:37], v[244:247], off
	s_nop 1
	v_add_u32_e32 v36, 0x90, v92
	v_ashrrev_i32_e32 v37, 31, v36
	v_lshlrev_b64 v[36:37], 8, v[36:37]
	v_lshl_add_u64 v[36:37], v[36:37], 0, s[12:13]
	v_lshl_add_u64 v[38:39], v[36:37], 0, s[92:93]
	v_lshlrev_b64 v[38:39], 8, v[38:39]
	v_lshl_add_u64 v[38:39], v[30:31], 0, v[38:39]
	v_lshl_add_u64 v[36:37], v[36:37], 0, s[14:15]
	v_cvt_pk_bf16_f32 v244, v164, v165
	v_cvt_pk_bf16_f32 v245, v166, v167
	v_cvt_pk_bf16_f32 v246, v168, v169
	v_cvt_pk_bf16_f32 v247, v170, v171
	v_lshl_add_u64 v[38:39], v[38:39], 0, v[228:229]
	s_nop 0
	v_permlane16_swap_b32_e32 v244, v246
	v_permlane16_swap_b32_e32 v245, v247
	global_store_dwordx4 v[38:39], v[244:247], off
	s_nop 1
	v_lshlrev_b64 v[36:37], 8, v[36:37]
	v_lshl_add_u64 v[36:37], v[30:31], 0, v[36:37]
	v_cvt_pk_bf16_f32 v244, v56, v57
	v_cvt_pk_bf16_f32 v245, v58, v59
	v_cvt_pk_bf16_f32 v246, v100, v101
	v_cvt_pk_bf16_f32 v247, v102, v103
	v_lshl_add_u64 v[36:37], v[36:37], 0, v[228:229]
	s_nop 0
	v_permlane16_swap_b32_e32 v244, v246
	v_permlane16_swap_b32_e32 v245, v247
	global_store_dwordx4 v[36:37], v[244:247], off
	s_nop 1
	v_add_u32_e32 v36, 0xa0, v92
	v_ashrrev_i32_e32 v37, 31, v36
	v_lshlrev_b64 v[36:37], 8, v[36:37]
	v_lshl_add_u64 v[36:37], v[36:37], 0, s[12:13]
	v_lshl_add_u64 v[38:39], v[36:37], 0, s[92:93]
	v_lshlrev_b64 v[38:39], 8, v[38:39]
	v_lshl_add_u64 v[38:39], v[30:31], 0, v[38:39]
	v_cvt_pk_bf16_f32 v244, v20, v21
	v_cvt_pk_bf16_f32 v245, v22, v23
	v_cvt_pk_bf16_f32 v246, v16, v17
	v_cvt_pk_bf16_f32 v247, v18, v19
	v_lshl_add_u64 v[38:39], v[38:39], 0, v[228:229]
	s_nop 0
	v_permlane16_swap_b32_e32 v244, v246
	v_permlane16_swap_b32_e32 v245, v247
	global_store_dwordx4 v[38:39], v[244:247], off
	s_nop 1
	v_lshl_add_u64 v[16:17], v[36:37], 0, s[14:15]
	v_lshlrev_b64 v[16:17], 8, v[16:17]
	v_lshl_add_u64 v[16:17], v[30:31], 0, v[16:17]
	v_cvt_pk_bf16_f32 v244, v104, v105
	v_cvt_pk_bf16_f32 v245, v106, v107
	v_cvt_pk_bf16_f32 v246, v112, v113
	v_cvt_pk_bf16_f32 v247, v114, v115
	v_lshl_add_u64 v[16:17], v[16:17], 0, v[228:229]
	s_nop 0
	v_permlane16_swap_b32_e32 v244, v246
	v_permlane16_swap_b32_e32 v245, v247
	global_store_dwordx4 v[16:17], v[244:247], off
	s_nop 1
	v_add_u32_e32 v16, 0xb0, v92
	v_ashrrev_i32_e32 v17, 31, v16
	v_lshlrev_b64 v[16:17], 8, v[16:17]
	v_lshl_add_u64 v[16:17], v[16:17], 0, s[12:13]
	v_lshl_add_u64 v[18:19], v[16:17], 0, s[92:93]
	v_lshlrev_b64 v[18:19], 8, v[18:19]
	v_lshl_add_u64 v[18:19], v[30:31], 0, v[18:19]
	v_cvt_pk_bf16_f32 v244, v4, v5
	v_cvt_pk_bf16_f32 v245, v6, v7
	v_cvt_pk_bf16_f32 v246, v0, v1
	v_cvt_pk_bf16_f32 v247, v2, v3
	v_lshl_add_u64 v[18:19], v[18:19], 0, v[228:229]
	s_nop 0
	v_permlane16_swap_b32_e32 v244, v246
	v_permlane16_swap_b32_e32 v245, v247
	global_store_dwordx4 v[18:19], v[244:247], off
	s_nop 1
	v_lshl_add_u64 v[0:1], v[16:17], 0, s[14:15]
	v_lshlrev_b64 v[0:1], 8, v[0:1]
	v_lshl_add_u64 v[0:1], v[30:31], 0, v[0:1]
	v_cvt_pk_bf16_f32 v244, v12, v13
	v_cvt_pk_bf16_f32 v245, v14, v15
	v_cvt_pk_bf16_f32 v246, v8, v9
	v_cvt_pk_bf16_f32 v247, v10, v11
	v_lshl_add_u64 v[0:1], v[0:1], 0, v[228:229]
	s_nop 0
	v_permlane16_swap_b32_e32 v244, v246
	v_permlane16_swap_b32_e32 v245, v247
	global_store_dwordx4 v[0:1], v[244:247], off
	s_nop 1
	s_add_i32 s34, s34, s90
	s_andn2_b64 vcc, exec, s[38:39]
	s_mov_b32 s12, s30
	s_mov_b32 s13, s35
	s_mov_b64 s[18:19], s[42:43]
	s_mov_b64 s[14:15], s[44:45]
	v_readlane_b32 s20, v255, 27
	s_cbranch_vccz .LBB0_97

.LBB0_104:
	s_ashr_i32 s42, s35, 7
	s_ashr_i32 s43, s42, 31
	s_ashr_i32 s13, s12, 31
	s_lshl_b64 s[42:43], s[42:43], 18
	s_lshl_b64 s[46:47], s[12:13], 17
	v_readlane_b32 s48, v254, 55
	v_readlane_b32 s49, v254, 56
	s_add_u32 s13, s48, s42
	s_addc_u32 s20, s49, s43
	s_add_u32 s42, s13, s46
	s_addc_u32 s43, s20, s47
	s_and_b64 s[40:41], s[40:41], exec
	s_cselect_b32 s41, s43, s15
	s_cselect_b32 s40, s42, s14
	s_add_i32 s37, 16, 0x10000
	v_add_u32_e32 v69, s37, v67
	ds_read_b128 v[0:3], v69
	ds_read_b128 v[4:7], v69 offset:1024
	ds_read_b128 v[8:11], v69 offset:2048
	ds_read_b128 v[12:15], v69 offset:3072
	s_add_u32 s48, s14, 0x10080
	s_addc_u32 s49, s15, 0
	s_add_i32 s46, s4, 0xc000
	v_lshl_add_u64 v[48:49], s[48:49], 0, v[62:63]
	s_mov_b32 m0, s46
	s_add_i32 s13, s4, 0xe000
	ds_read_b128 v[16:19], v68
	ds_read_b128 v[20:23], v68 offset:1024
	ds_read_b128 v[24:27], v68 offset:2048
	ds_read_b128 v[28:31], v68 offset:3072
	ds_read_b128 v[32:35], v68 offset:4096
	ds_read_b128 v[36:39], v68 offset:5120
	ds_read_b128 v[40:43], v68 offset:6144
	ds_read_b128 v[44:47], v68 offset:7168
	global_load_lds_dwordx4 v[48:49], off
	v_lshl_add_u64 v[48:49], s[48:49], 0, v[58:59]
	s_mov_b32 m0, s13
	s_nop 0
	global_load_lds_dwordx4 v[48:49], off
	s_waitcnt lgkmcnt(8)
	s_barrier
	s_waitcnt lgkmcnt(0)
	s_setprio 1
	s_waitcnt lgkmcnt(0)
	v_mfma_f32_16x16x32_bf16 v[48:51], v[0:3], v[16:19], 0
	v_mfma_f32_16x16x32_bf16 v[52:55], v[8:11], v[16:19], 0
	v_mfma_f32_16x16x32_bf16 v[70:73], v[0:3], v[24:27], 0
	v_mfma_f32_16x16x32_bf16 v[74:77], v[8:11], v[24:27], 0
	v_mfma_f32_16x16x32_bf16 v[78:81], v[0:3], v[32:35], 0
	v_mfma_f32_16x16x32_bf16 v[82:85], v[8:11], v[32:35], 0
	v_mfma_f32_16x16x32_bf16 v[86:89], v[0:3], v[40:43], 0
	v_mfma_f32_16x16x32_bf16 v[90:93], v[8:11], v[40:43], 0
	v_mfma_f32_16x16x32_bf16 v[48:51], v[4:7], v[20:23], v[48:51]
	v_mfma_f32_16x16x32_bf16 v[52:55], v[12:15], v[20:23], v[52:55]
	v_mfma_f32_16x16x32_bf16 v[70:73], v[4:7], v[28:31], v[70:73]
	v_mfma_f32_16x16x32_bf16 v[74:77], v[12:15], v[28:31], v[74:77]
	v_mfma_f32_16x16x32_bf16 v[78:81], v[4:7], v[36:39], v[78:81]
	v_mfma_f32_16x16x32_bf16 v[82:85], v[12:15], v[36:39], v[82:85]
	v_mfma_f32_16x16x32_bf16 v[86:89], v[4:7], v[44:47], v[86:89]
	v_mfma_f32_16x16x32_bf16 v[90:93], v[12:15], v[44:47], v[90:93]
	s_setprio 0
	s_barrier
	s_add_i32 s20, 16, 0x14000
	v_lshl_add_u64 v[64:65], s[18:19], 0, v[60:61]
	s_mov_b64 s[48:49], 0x100
	s_add_i32 s37, s37, s1
	v_add_u32_e32 v136, s20, v67
	v_lshl_add_u64 v[110:111], v[64:65], 0, s[48:49]
	s_mov_b32 m0, s37
	v_lshl_add_u64 v[126:127], s[18:19], 0, v[56:57]
	s_add_i32 s18, s37, 0x2000
	ds_read_b128 v[94:97], v136
	ds_read_b128 v[98:101], v136 offset:1024
	ds_read_b128 v[102:105], v136 offset:2048
	ds_read_b128 v[106:109], v136 offset:3072
	global_load_lds_dwordx4 v[110:111], off
	v_lshl_add_u64 v[110:111], v[126:127], 0, s[48:49]
	s_mov_b32 m0, s18
	s_nop 0
	global_load_lds_dwordx4 v[110:111], off
	s_barrier
	s_waitcnt lgkmcnt(0)
	s_setprio 1
	s_waitcnt lgkmcnt(0)
	v_mfma_f32_16x16x32_bf16 v[110:113], v[94:97], v[16:19], 0
	v_mfma_f32_16x16x32_bf16 v[16:19], v[102:105], v[16:19], 0
	v_mfma_f32_16x16x32_bf16 v[110:113], v[98:101], v[20:23], v[110:113]
	v_mfma_f32_16x16x32_bf16 v[16:19], v[106:109], v[20:23], v[16:19]
	v_mfma_f32_16x16x32_bf16 v[20:23], v[94:97], v[24:27], 0
	v_mfma_f32_16x16x32_bf16 v[24:27], v[102:105], v[24:27], 0
	v_mfma_f32_16x16x32_bf16 v[20:23], v[98:101], v[28:31], v[20:23]
	v_mfma_f32_16x16x32_bf16 v[24:27], v[106:109], v[28:31], v[24:27]
	v_mfma_f32_16x16x32_bf16 v[28:31], v[94:97], v[32:35], 0
	v_mfma_f32_16x16x32_bf16 v[32:35], v[102:105], v[32:35], 0
	v_mfma_f32_16x16x32_bf16 v[28:31], v[98:101], v[36:39], v[28:31]
	v_mfma_f32_16x16x32_bf16 v[32:35], v[106:109], v[36:39], v[32:35]
	v_mfma_f32_16x16x32_bf16 v[36:39], v[94:97], v[40:43], 0
	v_mfma_f32_16x16x32_bf16 v[40:43], v[102:105], v[40:43], 0
	v_mfma_f32_16x16x32_bf16 v[36:39], v[98:101], v[44:47], v[36:39]
	v_mfma_f32_16x16x32_bf16 v[40:43], v[106:109], v[44:47], v[40:43]
	s_setprio 0
	v_lshl_add_u64 v[130:131], s[14:15], 0, v[62:63]
	s_mov_b32 m0, s4
	v_lshl_add_u64 v[132:133], v[130:131], 0, s[48:49]
	s_barrier
	ds_read_b128 v[44:47], v68 offset:16384
	ds_read_b128 v[114:117], v68 offset:17408
	ds_read_b128 v[118:121], v68 offset:18432
	ds_read_b128 v[122:125], v68 offset:19456
	ds_read_b128 v[144:147], v68 offset:20480
	ds_read_b128 v[148:151], v68 offset:21504
	ds_read_b128 v[152:155], v68 offset:22528
	ds_read_b128 v[156:159], v68 offset:23552
	global_load_lds_dwordx4 v[132:133], off
	v_lshl_add_u64 v[132:133], s[14:15], 0, v[58:59]
	v_lshl_add_u64 v[134:135], v[132:133], 0, s[48:49]
	s_mov_b32 m0, s5
	s_nop 0
	global_load_lds_dwordx4 v[134:135], off
	s_barrier
	s_waitcnt lgkmcnt(0)
	s_setprio 1
	s_waitcnt lgkmcnt(0)
	v_mfma_f32_16x16x32_bf16 v[160:163], v[0:3], v[44:47], 0
	v_mfma_f32_16x16x32_bf16 v[168:171], v[0:3], v[118:121], 0
	v_mfma_f32_16x16x32_bf16 v[176:179], v[0:3], v[144:147], 0
	v_mfma_f32_16x16x32_bf16 v[0:3], v[0:3], v[152:155], 0
	v_mfma_f32_16x16x32_bf16 v[160:163], v[4:7], v[114:117], v[160:163]
	v_mfma_f32_16x16x32_bf16 v[164:167], v[8:11], v[44:47], 0
	v_mfma_f32_16x16x32_bf16 v[168:171], v[4:7], v[122:125], v[168:171]
	v_mfma_f32_16x16x32_bf16 v[172:175], v[8:11], v[118:121], 0
	v_mfma_f32_16x16x32_bf16 v[176:179], v[4:7], v[148:151], v[176:179]
	v_mfma_f32_16x16x32_bf16 v[180:183], v[8:11], v[144:147], 0
	v_mfma_f32_16x16x32_bf16 v[0:3], v[4:7], v[156:159], v[0:3]
	v_mfma_f32_16x16x32_bf16 v[4:7], v[8:11], v[152:155], 0
	v_mfma_f32_16x16x32_bf16 v[164:167], v[12:15], v[114:117], v[164:167]
	v_mfma_f32_16x16x32_bf16 v[172:175], v[12:15], v[122:125], v[172:175]
	v_mfma_f32_16x16x32_bf16 v[180:183], v[12:15], v[148:151], v[180:183]
	v_mfma_f32_16x16x32_bf16 v[4:7], v[12:15], v[156:159], v[4:7]
	s_setprio 0
	s_barrier
	s_mov_b64 s[48:49], 0x900
	s_add_i32 s20, s20, s1
	v_lshl_add_u64 v[8:9], v[64:65], 0, s[48:49]
	s_mov_b32 m0, s20
	s_add_i32 s19, s20, 0x2000
	global_load_lds_dwordx4 v[8:9], off
	v_lshl_add_u64 v[8:9], v[126:127], 0, s[48:49]
	s_mov_b32 m0, s19
	s_nop 0
	global_load_lds_dwordx4 v[8:9], off
	s_waitcnt vmcnt(6)
	s_barrier
	s_setprio 1
	v_mfma_f32_16x16x32_bf16 v[8:11], v[94:97], v[44:47], 0
	v_mfma_f32_16x16x32_bf16 v[12:15], v[102:105], v[44:47], 0
	v_mfma_f32_16x16x32_bf16 v[8:11], v[98:101], v[114:117], v[8:11]
	v_mfma_f32_16x16x32_bf16 v[12:15], v[106:109], v[114:117], v[12:15]
	v_mfma_f32_16x16x32_bf16 v[44:47], v[94:97], v[118:121], 0
	v_mfma_f32_16x16x32_bf16 v[114:117], v[102:105], v[118:121], 0
	v_mfma_f32_16x16x32_bf16 v[118:121], v[94:97], v[144:147], 0
	v_mfma_f32_16x16x32_bf16 v[94:97], v[94:97], v[152:155], 0
	v_mfma_f32_16x16x32_bf16 v[44:47], v[98:101], v[122:125], v[44:47]
	v_mfma_f32_16x16x32_bf16 v[114:117], v[106:109], v[122:125], v[114:117]
	v_mfma_f32_16x16x32_bf16 v[118:121], v[98:101], v[148:151], v[118:121]
	v_mfma_f32_16x16x32_bf16 v[122:125], v[102:105], v[144:147], 0
	v_mfma_f32_16x16x32_bf16 v[94:97], v[98:101], v[156:159], v[94:97]
	v_mfma_f32_16x16x32_bf16 v[98:101], v[102:105], v[152:155], 0
	v_mfma_f32_16x16x32_bf16 v[122:125], v[106:109], v[148:151], v[122:125]
	v_mfma_f32_16x16x32_bf16 v[98:101], v[106:109], v[156:159], v[98:101]
	s_setprio 0
	s_add_i32 s45, 16, 0x18000
	v_add_u32_e32 v137, s45, v67
	s_barrier
	ds_read_b128 v[102:105], v137
	ds_read_b128 v[106:109], v137 offset:1024
	ds_read_b128 v[144:147], v137 offset:2048
	ds_read_b128 v[148:151], v137 offset:3072
	s_add_u32 s48, s14, 0x10100
	s_addc_u32 s49, s15, 0
	s_mov_b32 m0, s16
	v_lshl_add_u64 v[134:135], s[48:49], 0, v[62:63]
	ds_read_b128 v[152:155], v68 offset:32768
	ds_read_b128 v[156:159], v68 offset:33792
	ds_read_b128 v[184:187], v68 offset:34816
	ds_read_b128 v[188:191], v68 offset:35840
	ds_read_b128 v[192:195], v68 offset:36864
	ds_read_b128 v[196:199], v68 offset:37888
	ds_read_b128 v[200:203], v68 offset:38912
	ds_read_b128 v[204:207], v68 offset:39936
	global_load_lds_dwordx4 v[134:135], off
	v_lshl_add_u64 v[134:135], s[48:49], 0, v[58:59]
	s_mov_b32 m0, s17
	s_nop 0
	global_load_lds_dwordx4 v[134:135], off
	s_waitcnt lgkmcnt(8)
	s_barrier
	s_waitcnt lgkmcnt(0)
	s_setprio 1
	s_waitcnt lgkmcnt(0)
	v_mfma_f32_16x16x32_bf16 v[48:51], v[102:105], v[152:155], v[48:51]
	v_mfma_f32_16x16x32_bf16 v[52:55], v[144:147], v[152:155], v[52:55]
	v_mfma_f32_16x16x32_bf16 v[70:73], v[102:105], v[184:187], v[70:73]
	v_mfma_f32_16x16x32_bf16 v[74:77], v[144:147], v[184:187], v[74:77]
	v_mfma_f32_16x16x32_bf16 v[78:81], v[102:105], v[192:195], v[78:81]
	v_mfma_f32_16x16x32_bf16 v[82:85], v[144:147], v[192:195], v[82:85]
	v_mfma_f32_16x16x32_bf16 v[86:89], v[102:105], v[200:203], v[86:89]
	v_mfma_f32_16x16x32_bf16 v[90:93], v[144:147], v[200:203], v[90:93]
	v_mfma_f32_16x16x32_bf16 v[48:51], v[106:109], v[156:159], v[48:51]
	v_mfma_f32_16x16x32_bf16 v[52:55], v[148:151], v[156:159], v[52:55]
	v_mfma_f32_16x16x32_bf16 v[70:73], v[106:109], v[188:191], v[70:73]
	v_mfma_f32_16x16x32_bf16 v[74:77], v[148:151], v[188:191], v[74:77]
	v_mfma_f32_16x16x32_bf16 v[78:81], v[106:109], v[196:199], v[78:81]
	v_mfma_f32_16x16x32_bf16 v[82:85], v[148:151], v[196:199], v[82:85]
	v_mfma_f32_16x16x32_bf16 v[86:89], v[106:109], v[204:207], v[86:89]
	v_mfma_f32_16x16x32_bf16 v[90:93], v[148:151], v[204:207], v[90:93]
	s_setprio 0
	s_barrier
	s_add_i32 s48, 16, 0x1c000
	s_mov_b64 s[50:51], 0x180
	s_add_i32 s49, s45, s1
	v_add_u32_e32 v138, s48, v67
	v_lshl_add_u64 v[134:135], v[64:65], 0, s[50:51]
	s_mov_b32 m0, s49
	s_add_i32 s45, s49, 0x2000
	ds_read_b128 v[208:211], v138
	ds_read_b128 v[212:215], v138 offset:1024
	ds_read_b128 v[216:219], v138 offset:2048
	ds_read_b128 v[220:223], v138 offset:3072
	global_load_lds_dwordx4 v[134:135], off
	v_lshl_add_u64 v[134:135], v[126:127], 0, s[50:51]
	s_mov_b32 m0, s45
	s_nop 0
	global_load_lds_dwordx4 v[134:135], off
	s_barrier
	s_waitcnt lgkmcnt(0)
	s_setprio 1
	s_waitcnt lgkmcnt(0)
	v_mfma_f32_16x16x32_bf16 v[110:113], v[208:211], v[152:155], v[110:113]
	v_mfma_f32_16x16x32_bf16 v[16:19], v[216:219], v[152:155], v[16:19]
	v_mfma_f32_16x16x32_bf16 v[20:23], v[208:211], v[184:187], v[20:23]
	v_mfma_f32_16x16x32_bf16 v[24:27], v[216:219], v[184:187], v[24:27]
	v_mfma_f32_16x16x32_bf16 v[28:31], v[208:211], v[192:195], v[28:31]
	v_mfma_f32_16x16x32_bf16 v[32:35], v[216:219], v[192:195], v[32:35]
	v_mfma_f32_16x16x32_bf16 v[36:39], v[208:211], v[200:203], v[36:39]
	v_mfma_f32_16x16x32_bf16 v[40:43], v[216:219], v[200:203], v[40:43]
	v_mfma_f32_16x16x32_bf16 v[110:113], v[212:215], v[156:159], v[110:113]
	v_mfma_f32_16x16x32_bf16 v[16:19], v[220:223], v[156:159], v[16:19]
	v_mfma_f32_16x16x32_bf16 v[20:23], v[212:215], v[188:191], v[20:23]
	v_mfma_f32_16x16x32_bf16 v[24:27], v[220:223], v[188:191], v[24:27]
	v_mfma_f32_16x16x32_bf16 v[28:31], v[212:215], v[196:199], v[28:31]
	v_mfma_f32_16x16x32_bf16 v[32:35], v[220:223], v[196:199], v[32:35]
	v_mfma_f32_16x16x32_bf16 v[36:39], v[212:215], v[204:207], v[36:39]
	v_mfma_f32_16x16x32_bf16 v[40:43], v[220:223], v[204:207], v[40:43]
	s_setprio 0
	s_mov_b32 m0, s24
	v_lshl_add_u64 v[130:131], v[130:131], 0, s[50:51]
	s_barrier
	ds_read_b128 v[152:155], v68 offset:49152
	ds_read_b128 v[156:159], v68 offset:50176
	ds_read_b128 v[184:187], v68 offset:51200
	ds_read_b128 v[188:191], v68 offset:52224
	ds_read_b128 v[192:195], v68 offset:53248
	ds_read_b128 v[196:199], v68 offset:54272
	ds_read_b128 v[200:203], v68 offset:55296
	ds_read_b128 v[204:207], v68 offset:56320
	global_load_lds_dwordx4 v[130:131], off
	v_lshl_add_u64 v[130:131], v[132:133], 0, s[50:51]
	s_mov_b32 m0, s25
	s_nop 0
	global_load_lds_dwordx4 v[130:131], off
	s_barrier
	s_waitcnt lgkmcnt(0)
	s_setprio 1
	s_waitcnt lgkmcnt(0)
	v_mfma_f32_16x16x32_bf16 v[160:163], v[102:105], v[152:155], v[160:163]
	v_mfma_f32_16x16x32_bf16 v[164:167], v[144:147], v[152:155], v[164:167]
	v_mfma_f32_16x16x32_bf16 v[168:171], v[102:105], v[184:187], v[168:171]
	v_mfma_f32_16x16x32_bf16 v[172:175], v[144:147], v[184:187], v[172:175]
	v_mfma_f32_16x16x32_bf16 v[176:179], v[102:105], v[192:195], v[176:179]
	v_mfma_f32_16x16x32_bf16 v[180:183], v[144:147], v[192:195], v[180:183]
	v_mfma_f32_16x16x32_bf16 v[0:3], v[102:105], v[200:203], v[0:3]
	v_mfma_f32_16x16x32_bf16 v[4:7], v[144:147], v[200:203], v[4:7]
	v_mfma_f32_16x16x32_bf16 v[160:163], v[106:109], v[156:159], v[160:163]
	v_mfma_f32_16x16x32_bf16 v[164:167], v[148:151], v[156:159], v[164:167]
	v_mfma_f32_16x16x32_bf16 v[168:171], v[106:109], v[188:191], v[168:171]
	v_mfma_f32_16x16x32_bf16 v[172:175], v[148:151], v[188:191], v[172:175]
	v_mfma_f32_16x16x32_bf16 v[176:179], v[106:109], v[196:199], v[176:179]
	v_mfma_f32_16x16x32_bf16 v[180:183], v[148:151], v[196:199], v[180:183]
	v_mfma_f32_16x16x32_bf16 v[0:3], v[106:109], v[204:207], v[0:3]
	v_mfma_f32_16x16x32_bf16 v[4:7], v[148:151], v[204:207], v[4:7]
	s_setprio 0
	s_barrier
	s_mov_b64 s[50:51], 0x980
	s_add_i32 s48, s48, s1
	v_lshl_add_u64 v[64:65], v[64:65], 0, s[50:51]
	s_mov_b32 m0, s48
	s_add_i32 s47, s48, 0x2000
	global_load_lds_dwordx4 v[64:65], off
	v_lshl_add_u64 v[64:65], v[126:127], 0, s[50:51]
	s_mov_b32 m0, s47
	s_nop 0
	global_load_lds_dwordx4 v[64:65], off
	s_waitcnt vmcnt(6)
	s_barrier
	s_setprio 1
	v_mfma_f32_16x16x32_bf16 v[8:11], v[208:211], v[152:155], v[8:11]
	v_mfma_f32_16x16x32_bf16 v[12:15], v[216:219], v[152:155], v[12:15]
	v_mfma_f32_16x16x32_bf16 v[44:47], v[208:211], v[184:187], v[44:47]
	v_mfma_f32_16x16x32_bf16 v[102:105], v[216:219], v[184:187], v[114:117]
	v_mfma_f32_16x16x32_bf16 v[106:109], v[208:211], v[192:195], v[118:121]
	v_mfma_f32_16x16x32_bf16 v[114:117], v[216:219], v[192:195], v[122:125]
	v_mfma_f32_16x16x32_bf16 v[94:97], v[208:211], v[200:203], v[94:97]
	v_mfma_f32_16x16x32_bf16 v[98:101], v[216:219], v[200:203], v[98:101]
	v_mfma_f32_16x16x32_bf16 v[8:11], v[212:215], v[156:159], v[8:11]
	v_mfma_f32_16x16x32_bf16 v[12:15], v[220:223], v[156:159], v[12:15]
	v_mfma_f32_16x16x32_bf16 v[44:47], v[212:215], v[188:191], v[44:47]
	v_mfma_f32_16x16x32_bf16 v[102:105], v[220:223], v[188:191], v[102:105]
	v_mfma_f32_16x16x32_bf16 v[106:109], v[212:215], v[196:199], v[106:109]
	v_mfma_f32_16x16x32_bf16 v[114:117], v[220:223], v[196:199], v[114:117]
	v_mfma_f32_16x16x32_bf16 v[94:97], v[212:215], v[204:207], v[94:97]
	v_mfma_f32_16x16x32_bf16 v[98:101], v[220:223], v[204:207], v[98:101]
	s_setprio 0
	s_barrier
	ds_read_b128 v[118:121], v69
	ds_read_b128 v[122:125], v69 offset:1024
	ds_read_b128 v[144:147], v69 offset:2048
	ds_read_b128 v[148:151], v69 offset:3072
	s_add_u32 s14, s14, 0x10180
	s_addc_u32 s15, s15, 0
	s_mov_b32 m0, s46
	v_lshl_add_u64 v[64:65], s[14:15], 0, v[62:63]
	ds_read_b128 v[152:155], v68
	ds_read_b128 v[156:159], v68 offset:1024
	ds_read_b128 v[184:187], v68 offset:2048
	ds_read_b128 v[188:191], v68 offset:3072
	ds_read_b128 v[192:195], v68 offset:4096
	ds_read_b128 v[196:199], v68 offset:5120
	ds_read_b128 v[200:203], v68 offset:6144
	ds_read_b128 v[204:207], v68 offset:7168
	global_load_lds_dwordx4 v[64:65], off
	v_lshl_add_u64 v[64:65], s[14:15], 0, v[58:59]
	s_mov_b32 m0, s13
	s_nop 0
	global_load_lds_dwordx4 v[64:65], off
	s_waitcnt lgkmcnt(8)
	s_barrier
	s_waitcnt lgkmcnt(0)
	s_setprio 1
	s_waitcnt lgkmcnt(0)
	v_mfma_f32_16x16x32_bf16 v[48:51], v[118:121], v[152:155], v[48:51]
	v_mfma_f32_16x16x32_bf16 v[52:55], v[144:147], v[152:155], v[52:55]
	v_mfma_f32_16x16x32_bf16 v[70:73], v[118:121], v[184:187], v[70:73]
	v_mfma_f32_16x16x32_bf16 v[74:77], v[144:147], v[184:187], v[74:77]
	v_mfma_f32_16x16x32_bf16 v[78:81], v[118:121], v[192:195], v[78:81]
	v_mfma_f32_16x16x32_bf16 v[82:85], v[144:147], v[192:195], v[82:85]
	v_mfma_f32_16x16x32_bf16 v[86:89], v[118:121], v[200:203], v[86:89]
	v_mfma_f32_16x16x32_bf16 v[90:93], v[144:147], v[200:203], v[90:93]
	v_mfma_f32_16x16x32_bf16 v[48:51], v[122:125], v[156:159], v[48:51]
	v_mfma_f32_16x16x32_bf16 v[52:55], v[148:151], v[156:159], v[52:55]
	v_mfma_f32_16x16x32_bf16 v[70:73], v[122:125], v[188:191], v[70:73]
	v_mfma_f32_16x16x32_bf16 v[74:77], v[148:151], v[188:191], v[74:77]
	v_mfma_f32_16x16x32_bf16 v[78:81], v[122:125], v[196:199], v[78:81]
	v_mfma_f32_16x16x32_bf16 v[82:85], v[148:151], v[196:199], v[82:85]
	v_mfma_f32_16x16x32_bf16 v[86:89], v[122:125], v[204:207], v[86:89]
	v_mfma_f32_16x16x32_bf16 v[90:93], v[148:151], v[204:207], v[90:93]
	s_setprio 0
	s_barrier
	s_mov_b32 m0, s37
	v_lshl_add_u64 v[64:65], s[30:31], 0, v[60:61]
	ds_read_b128 v[208:211], v136
	ds_read_b128 v[212:215], v136 offset:1024
	ds_read_b128 v[216:219], v136 offset:2048
	ds_read_b128 v[220:223], v136 offset:3072
	global_load_lds_dwordx4 v[64:65], off
	v_lshl_add_u64 v[126:127], s[30:31], 0, v[56:57]
	s_mov_b32 m0, s18
	s_nop 0
	global_load_lds_dwordx4 v[126:127], off
	s_barrier
	s_waitcnt lgkmcnt(0)
	s_setprio 1
	s_waitcnt lgkmcnt(0)
	v_mfma_f32_16x16x32_bf16 v[110:113], v[208:211], v[152:155], v[110:113]
	v_mfma_f32_16x16x32_bf16 v[16:19], v[216:219], v[152:155], v[16:19]
	v_mfma_f32_16x16x32_bf16 v[20:23], v[208:211], v[184:187], v[20:23]
	v_mfma_f32_16x16x32_bf16 v[24:27], v[216:219], v[184:187], v[24:27]
	v_mfma_f32_16x16x32_bf16 v[28:31], v[208:211], v[192:195], v[28:31]
	v_mfma_f32_16x16x32_bf16 v[32:35], v[216:219], v[192:195], v[32:35]
	v_mfma_f32_16x16x32_bf16 v[36:39], v[208:211], v[200:203], v[36:39]
	v_mfma_f32_16x16x32_bf16 v[40:43], v[216:219], v[200:203], v[40:43]
	v_mfma_f32_16x16x32_bf16 v[110:113], v[212:215], v[156:159], v[110:113]
	v_mfma_f32_16x16x32_bf16 v[16:19], v[220:223], v[156:159], v[16:19]
	v_mfma_f32_16x16x32_bf16 v[20:23], v[212:215], v[188:191], v[20:23]
	v_mfma_f32_16x16x32_bf16 v[24:27], v[220:223], v[188:191], v[24:27]
	v_mfma_f32_16x16x32_bf16 v[28:31], v[212:215], v[196:199], v[28:31]
	v_mfma_f32_16x16x32_bf16 v[32:35], v[220:223], v[196:199], v[32:35]
	v_mfma_f32_16x16x32_bf16 v[36:39], v[212:215], v[204:207], v[36:39]
	v_mfma_f32_16x16x32_bf16 v[40:43], v[220:223], v[204:207], v[40:43]
	s_setprio 0
	s_mov_b32 m0, s4
	v_lshl_add_u64 v[130:131], s[40:41], 0, v[62:63]
	s_barrier
	ds_read_b128 v[152:155], v68 offset:16384
	ds_read_b128 v[156:159], v68 offset:17408
	ds_read_b128 v[184:187], v68 offset:18432
	ds_read_b128 v[188:191], v68 offset:19456
	ds_read_b128 v[192:195], v68 offset:20480
	ds_read_b128 v[196:199], v68 offset:21504
	ds_read_b128 v[200:203], v68 offset:22528
	ds_read_b128 v[204:207], v68 offset:23552
	global_load_lds_dwordx4 v[130:131], off
	v_lshl_add_u64 v[132:133], s[40:41], 0, v[58:59]
	s_mov_b32 m0, s5
	s_nop 0
	global_load_lds_dwordx4 v[132:133], off
	s_barrier
	s_waitcnt lgkmcnt(0)
	s_setprio 1
	s_waitcnt lgkmcnt(0)
	v_mfma_f32_16x16x32_bf16 v[160:163], v[118:121], v[152:155], v[160:163]
	v_mfma_f32_16x16x32_bf16 v[164:167], v[144:147], v[152:155], v[164:167]
	v_mfma_f32_16x16x32_bf16 v[168:171], v[118:121], v[184:187], v[168:171]
	v_mfma_f32_16x16x32_bf16 v[172:175], v[144:147], v[184:187], v[172:175]
	v_mfma_f32_16x16x32_bf16 v[176:179], v[118:121], v[192:195], v[176:179]
	v_mfma_f32_16x16x32_bf16 v[180:183], v[144:147], v[192:195], v[180:183]
	v_mfma_f32_16x16x32_bf16 v[0:3], v[118:121], v[200:203], v[0:3]
	v_mfma_f32_16x16x32_bf16 v[4:7], v[144:147], v[200:203], v[4:7]
	v_mfma_f32_16x16x32_bf16 v[160:163], v[122:125], v[156:159], v[160:163]
	v_mfma_f32_16x16x32_bf16 v[164:167], v[148:151], v[156:159], v[164:167]
	v_mfma_f32_16x16x32_bf16 v[168:171], v[122:125], v[188:191], v[168:171]
	v_mfma_f32_16x16x32_bf16 v[172:175], v[148:151], v[188:191], v[172:175]
	v_mfma_f32_16x16x32_bf16 v[176:179], v[122:125], v[196:199], v[176:179]
	v_mfma_f32_16x16x32_bf16 v[180:183], v[148:151], v[196:199], v[180:183]
	v_mfma_f32_16x16x32_bf16 v[0:3], v[122:125], v[204:207], v[0:3]
	v_mfma_f32_16x16x32_bf16 v[118:121], v[148:151], v[204:207], v[4:7]
	s_setprio 0
	s_barrier
	s_mov_b64 s[14:15], 0x800
	s_mov_b32 m0, s20
	v_lshl_add_u64 v[4:5], v[64:65], 0, s[14:15]
	global_load_lds_dwordx4 v[4:5], off
	v_lshl_add_u64 v[4:5], v[126:127], 0, s[14:15]
	s_mov_b32 m0, s19
	s_nop 0
	global_load_lds_dwordx4 v[4:5], off
	s_waitcnt vmcnt(6)
	s_barrier
	s_setprio 1
	v_mfma_f32_16x16x32_bf16 v[4:7], v[208:211], v[152:155], v[8:11]
	v_mfma_f32_16x16x32_bf16 v[8:11], v[212:215], v[156:159], v[4:7]
	v_mfma_f32_16x16x32_bf16 v[4:7], v[216:219], v[152:155], v[12:15]
	v_mfma_f32_16x16x32_bf16 v[12:15], v[220:223], v[156:159], v[4:7]
	v_mfma_f32_16x16x32_bf16 v[4:7], v[208:211], v[184:187], v[44:47]
	v_mfma_f32_16x16x32_bf16 v[44:47], v[212:215], v[188:191], v[4:7]
	v_mfma_f32_16x16x32_bf16 v[4:7], v[216:219], v[184:187], v[102:105]
	v_mfma_f32_16x16x32_bf16 v[102:105], v[220:223], v[188:191], v[4:7]
	v_mfma_f32_16x16x32_bf16 v[4:7], v[208:211], v[192:195], v[106:109]
	v_mfma_f32_16x16x32_bf16 v[106:109], v[212:215], v[196:199], v[4:7]
	v_mfma_f32_16x16x32_bf16 v[4:7], v[216:219], v[192:195], v[114:117]
	v_mfma_f32_16x16x32_bf16 v[114:117], v[220:223], v[196:199], v[4:7]
	v_mfma_f32_16x16x32_bf16 v[4:7], v[208:211], v[200:203], v[94:97]
	v_mfma_f32_16x16x32_bf16 v[94:97], v[212:215], v[204:207], v[4:7]
	v_mfma_f32_16x16x32_bf16 v[4:7], v[216:219], v[200:203], v[98:101]
	v_mfma_f32_16x16x32_bf16 v[98:101], v[220:223], v[204:207], v[4:7]
	s_setprio 0
	s_barrier
	s_nop 4
	ds_read_b128 v[4:7], v137
	ds_read_b128 v[122:125], v137 offset:1024
	ds_read_b128 v[144:147], v137 offset:2048
	ds_read_b128 v[148:151], v137 offset:3072
	s_add_u32 s14, s40, 0x10000
	s_addc_u32 s15, s41, 0
	s_mov_b32 m0, s16
	v_lshl_add_u64 v[134:135], s[14:15], 0, v[62:63]
	ds_read_b128 v[152:155], v68 offset:32768
	ds_read_b128 v[156:159], v68 offset:33792
	ds_read_b128 v[184:187], v68 offset:34816
	ds_read_b128 v[188:191], v68 offset:35840
	ds_read_b128 v[192:195], v68 offset:36864
	ds_read_b128 v[196:199], v68 offset:37888
	ds_read_b128 v[200:203], v68 offset:38912
	ds_read_b128 v[204:207], v68 offset:39936
	global_load_lds_dwordx4 v[134:135], off
	v_lshl_add_u64 v[134:135], s[14:15], 0, v[58:59]
	s_mov_b32 m0, s17
	s_nop 0
	global_load_lds_dwordx4 v[134:135], off
	s_waitcnt lgkmcnt(8)
	s_barrier
	s_waitcnt lgkmcnt(0)
	s_setprio 1
	s_waitcnt lgkmcnt(0)
	v_mfma_f32_16x16x32_bf16 v[48:51], v[4:7], v[152:155], v[48:51]
	v_mfma_f32_16x16x32_bf16 v[208:211], v[122:125], v[156:159], v[48:51]
	v_mfma_f32_16x16x32_bf16 v[48:51], v[144:147], v[152:155], v[52:55]
	v_mfma_f32_16x16x32_bf16 v[212:215], v[148:151], v[156:159], v[48:51]
	v_mfma_f32_16x16x32_bf16 v[48:51], v[4:7], v[184:187], v[70:73]
	v_mfma_f32_16x16x32_bf16 v[70:73], v[122:125], v[188:191], v[48:51]
	v_mfma_f32_16x16x32_bf16 v[48:51], v[144:147], v[184:187], v[74:77]
	v_mfma_f32_16x16x32_bf16 v[74:77], v[148:151], v[188:191], v[48:51]
	v_mfma_f32_16x16x32_bf16 v[48:51], v[4:7], v[192:195], v[78:81]
	v_mfma_f32_16x16x32_bf16 v[78:81], v[122:125], v[196:199], v[48:51]
	v_mfma_f32_16x16x32_bf16 v[48:51], v[144:147], v[192:195], v[82:85]
	v_mfma_f32_16x16x32_bf16 v[82:85], v[148:151], v[196:199], v[48:51]
	v_mfma_f32_16x16x32_bf16 v[48:51], v[4:7], v[200:203], v[86:89]
	v_mfma_f32_16x16x32_bf16 v[52:55], v[122:125], v[204:207], v[48:51]
	v_mfma_f32_16x16x32_bf16 v[48:51], v[144:147], v[200:203], v[90:93]
	v_mfma_f32_16x16x32_bf16 v[48:51], v[148:151], v[204:207], v[48:51]
	s_setprio 0
	s_barrier
	s_mov_b32 m0, s49
	v_lshl_add_u64 v[134:135], v[64:65], 0, s[28:29]
	ds_read_b128 v[86:89], v138
	ds_read_b128 v[90:93], v138 offset:1024
	ds_read_b128 v[216:219], v138 offset:2048
	ds_read_b128 v[220:223], v138 offset:3072
	global_load_lds_dwordx4 v[134:135], off
	v_lshl_add_u64 v[134:135], v[126:127], 0, s[28:29]
	s_mov_b32 m0, s45
	s_nop 0
	global_load_lds_dwordx4 v[134:135], off
	s_barrier
	s_waitcnt lgkmcnt(0)
	s_setprio 1
	s_waitcnt lgkmcnt(0)
	v_mfma_f32_16x16x32_bf16 v[16:19], v[216:219], v[152:155], v[16:19]
	v_mfma_f32_16x16x32_bf16 v[110:113], v[86:89], v[152:155], v[110:113]
	v_mfma_f32_16x16x32_bf16 v[152:155], v[220:223], v[156:159], v[16:19]
	v_mfma_f32_16x16x32_bf16 v[16:19], v[86:89], v[184:187], v[20:23]
	v_mfma_f32_16x16x32_bf16 v[110:113], v[90:93], v[156:159], v[110:113]
	v_mfma_f32_16x16x32_bf16 v[156:159], v[90:93], v[188:191], v[16:19]
	v_mfma_f32_16x16x32_bf16 v[16:19], v[216:219], v[184:187], v[24:27]
	v_mfma_f32_16x16x32_bf16 v[184:187], v[220:223], v[188:191], v[16:19]
	v_mfma_f32_16x16x32_bf16 v[16:19], v[86:89], v[192:195], v[28:31]
	v_mfma_f32_16x16x32_bf16 v[188:191], v[90:93], v[196:199], v[16:19]
	v_mfma_f32_16x16x32_bf16 v[16:19], v[216:219], v[192:195], v[32:35]
	v_mfma_f32_16x16x32_bf16 v[192:195], v[220:223], v[196:199], v[16:19]
	v_mfma_f32_16x16x32_bf16 v[16:19], v[86:89], v[200:203], v[36:39]
	v_mfma_f32_16x16x32_bf16 v[196:199], v[90:93], v[204:207], v[16:19]
	v_mfma_f32_16x16x32_bf16 v[16:19], v[216:219], v[200:203], v[40:43]
	v_mfma_f32_16x16x32_bf16 v[200:203], v[220:223], v[204:207], v[16:19]
	s_setprio 0
	s_mov_b32 m0, s24
	s_nop 4
	v_lshl_add_u64 v[16:17], v[130:131], 0, s[28:29]
	s_barrier
	ds_read_b128 v[24:27], v68 offset:49152
	ds_read_b128 v[28:31], v68 offset:50176
	ds_read_b128 v[40:43], v68 offset:51200
	ds_read_b128 v[204:207], v68 offset:52224
	ds_read_b128 v[224:227], v68 offset:53248
	ds_read_b128 v[228:231], v68 offset:54272
	ds_read_b128 v[244:247], v68 offset:55296
	ds_read_b128 v[248:251], v68 offset:56320
	global_load_lds_dwordx4 v[16:17], off
	v_lshl_add_u64 v[16:17], v[132:133], 0, s[28:29]
	s_mov_b32 m0, s25
	s_nop 0
	global_load_lds_dwordx4 v[16:17], off
	s_barrier
	s_waitcnt lgkmcnt(0)
	s_setprio 1
	s_waitcnt lgkmcnt(0)
	v_mfma_f32_16x16x32_bf16 v[16:19], v[4:7], v[24:27], v[160:163]
	v_mfma_f32_16x16x32_bf16 v[160:163], v[122:125], v[28:31], v[16:19]
	v_mfma_f32_16x16x32_bf16 v[16:19], v[144:147], v[24:27], v[164:167]
	v_mfma_f32_16x16x32_bf16 v[164:167], v[148:151], v[28:31], v[16:19]
	v_mfma_f32_16x16x32_bf16 v[16:19], v[4:7], v[40:43], v[168:171]
	v_mfma_f32_16x16x32_bf16 v[36:39], v[122:125], v[204:207], v[16:19]
	v_mfma_f32_16x16x32_bf16 v[16:19], v[144:147], v[40:43], v[172:175]
	v_mfma_f32_16x16x32_bf16 v[32:35], v[148:151], v[204:207], v[16:19]
	v_mfma_f32_16x16x32_bf16 v[16:19], v[4:7], v[224:227], v[176:179]
	v_mfma_f32_16x16x32_bf16 v[0:3], v[4:7], v[244:247], v[0:3]
	v_mfma_f32_16x16x32_bf16 v[20:23], v[122:125], v[228:231], v[16:19]
	v_mfma_f32_16x16x32_bf16 v[16:19], v[144:147], v[224:227], v[180:183]
	v_mfma_f32_16x16x32_bf16 v[4:7], v[122:125], v[248:251], v[0:3]
	v_mfma_f32_16x16x32_bf16 v[0:3], v[144:147], v[244:247], v[118:121]
	v_mfma_f32_16x16x32_bf16 v[16:19], v[148:151], v[228:231], v[16:19]
	v_mfma_f32_16x16x32_bf16 v[0:3], v[148:151], v[248:251], v[0:3]
	s_setprio 0
	s_barrier
	s_mov_b64 s[14:15], 0x880
	s_mov_b32 m0, s48
	v_lshl_add_u64 v[64:65], v[64:65], 0, s[14:15]
	global_load_lds_dwordx4 v[64:65], off
	v_lshl_add_u64 v[64:65], v[126:127], 0, s[14:15]
	s_mov_b32 m0, s47
	s_nop 0
	global_load_lds_dwordx4 v[64:65], off
	s_waitcnt vmcnt(6)
	s_barrier
	s_setprio 1
	v_mfma_f32_16x16x32_bf16 v[8:11], v[86:89], v[24:27], v[8:11]
	v_mfma_f32_16x16x32_bf16 v[118:121], v[90:93], v[28:31], v[8:11]
	v_mfma_f32_16x16x32_bf16 v[8:11], v[216:219], v[24:27], v[12:15]
	v_mfma_f32_16x16x32_bf16 v[122:125], v[220:223], v[28:31], v[8:11]
	v_mfma_f32_16x16x32_bf16 v[8:11], v[86:89], v[40:43], v[44:47]
	v_mfma_f32_16x16x32_bf16 v[44:47], v[90:93], v[204:207], v[8:11]
	v_mfma_f32_16x16x32_bf16 v[8:11], v[216:219], v[40:43], v[102:105]
	v_mfma_f32_16x16x32_bf16 v[40:43], v[220:223], v[204:207], v[8:11]
	v_mfma_f32_16x16x32_bf16 v[8:11], v[86:89], v[224:227], v[106:109]
	v_mfma_f32_16x16x32_bf16 v[28:31], v[90:93], v[228:231], v[8:11]
	v_mfma_f32_16x16x32_bf16 v[8:11], v[216:219], v[224:227], v[114:117]
	v_mfma_f32_16x16x32_bf16 v[24:27], v[220:223], v[228:231], v[8:11]
	v_mfma_f32_16x16x32_bf16 v[8:11], v[86:89], v[244:247], v[94:97]
	v_mfma_f32_16x16x32_bf16 v[12:15], v[90:93], v[248:251], v[8:11]
	v_mfma_f32_16x16x32_bf16 v[8:11], v[216:219], v[244:247], v[98:101]
	v_mfma_f32_16x16x32_bf16 v[8:11], v[220:223], v[248:251], v[8:11]
	v_mbcnt_lo_u32_b32 v140, -1, 0
	v_mbcnt_hi_u32_b32 v140, -1, v140
	v_and_b32_e32 v140, 16, v140
	v_lshrrev_b32_e32 v141, 1, v140
	v_add_u32_e32 v140, v140, v141
	v_mov_b32_e32 v141, 0
	s_setprio 0
	s_lshl_b32 s14, s36, 1
	s_and_b32 s13, s14, 0xffffff00
	v_add_u32_e32 v64, s13, v66
	v_ashrrev_i32_e32 v65, 31, v64
	s_and_b32 s18, s14, 0xf0
	v_lshlrev_b64 v[86:87], 8, v[64:65]
	s_and_b32 s13, s14, 14
	v_or_b32_e32 v65, s18, v86
	v_or_b32_e32 v86, s13, v65
	s_ashr_i32 s45, s44, 31
	v_lshlrev_b64 v[88:89], 9, v[86:87]
	s_or_b32 s19, s13, 1
	s_lshl_b64 s[14:15], s[44:45], 8
	v_lshl_add_u64 v[88:89], s[96:97], 0, v[88:89]
	v_or_b32_e32 v86, s19, v65
	v_lshl_add_u64 v[88:89], v[88:89], 0, s[14:15]
	v_lshlrev_b64 v[86:87], 9, v[86:87]
	v_lshl_add_u64 v[88:89], v[88:89], 0, s[92:93]
	v_lshl_add_u64 v[86:87], s[96:97], 0, v[86:87]
	v_lshl_add_u64 v[88:89], v[88:89], 0, v[128:129]
	v_lshl_add_u64 v[86:87], v[86:87], 0, s[14:15]
	s_barrier
	v_cvt_pk_bf16_f32 v238, v208, v209
	v_cvt_pk_bf16_f32 v239, v210, v211
	v_cvt_pk_bf16_f32 v240, v212, v213
	v_cvt_pk_bf16_f32 v241, v214, v215
	v_lshl_add_u64 v[88:89], v[88:89], 0, v[140:141]
	s_nop 0
	v_permlane16_swap_b32_e32 v238, v240
	v_permlane16_swap_b32_e32 v239, v241
	global_store_dwordx4 v[88:89], v[238:241], off
	s_nop 1
	v_lshl_add_u64 v[86:87], v[86:87], 0, s[92:93]
	v_lshl_add_u64 v[86:87], v[86:87], 0, v[128:129]
	v_cvt_pk_bf16_f32 v238, v110, v111
	v_cvt_pk_bf16_f32 v239, v112, v113
	v_cvt_pk_bf16_f32 v240, v152, v153
	v_cvt_pk_bf16_f32 v241, v154, v155
	v_lshl_add_u64 v[86:87], v[86:87], 0, v[140:141]
	s_nop 0
	v_permlane16_swap_b32_e32 v238, v240
	v_permlane16_swap_b32_e32 v239, v241
	global_store_dwordx4 v[86:87], v[238:241], off
	s_nop 1
	v_or_b32_e32 v86, 16, v64
	v_ashrrev_i32_e32 v87, 31, v86
	v_lshlrev_b64 v[86:87], 8, v[86:87]
	v_or_b32_e32 v65, s18, v86
	v_or_b32_e32 v86, s13, v65
	v_lshlrev_b64 v[88:89], 9, v[86:87]
	v_lshl_add_u64 v[88:89], s[96:97], 0, v[88:89]
	v_lshl_add_u64 v[88:89], v[88:89], 0, s[14:15]
	v_lshl_add_u64 v[88:89], v[88:89], 0, s[92:93]
	v_lshl_add_u64 v[88:89], v[88:89], 0, v[128:129]
	v_cvt_pk_bf16_f32 v238, v70, v71
	v_cvt_pk_bf16_f32 v239, v72, v73
	v_cvt_pk_bf16_f32 v240, v74, v75
	v_cvt_pk_bf16_f32 v241, v76, v77
	v_lshl_add_u64 v[88:89], v[88:89], 0, v[140:141]
	s_nop 0
	v_permlane16_swap_b32_e32 v238, v240
	v_permlane16_swap_b32_e32 v239, v241
	global_store_dwordx4 v[88:89], v[238:241], off
	s_nop 1
	v_or_b32_e32 v86, s19, v65
	v_lshlrev_b64 v[70:71], 9, v[86:87]
	v_lshl_add_u64 v[70:71], s[96:97], 0, v[70:71]
	v_lshl_add_u64 v[70:71], v[70:71], 0, s[14:15]
	v_lshl_add_u64 v[70:71], v[70:71], 0, s[92:93]
	v_lshl_add_u64 v[70:71], v[70:71], 0, v[128:129]
	v_cvt_pk_bf16_f32 v238, v156, v157
	v_cvt_pk_bf16_f32 v239, v158, v159
	v_cvt_pk_bf16_f32 v240, v184, v185
	v_cvt_pk_bf16_f32 v241, v186, v187
	v_lshl_add_u64 v[70:71], v[70:71], 0, v[140:141]
	s_nop 0
	v_permlane16_swap_b32_e32 v238, v240
	v_permlane16_swap_b32_e32 v239, v241
	global_store_dwordx4 v[70:71], v[238:241], off
	s_nop 1
	v_or_b32_e32 v70, 32, v64
	v_ashrrev_i32_e32 v71, 31, v70
	v_lshlrev_b64 v[70:71], 8, v[70:71]
	v_or_b32_e32 v65, s18, v70
	v_or_b32_e32 v70, s13, v65
	v_lshlrev_b64 v[72:73], 9, v[70:71]
	v_lshl_add_u64 v[72:73], s[96:97], 0, v[72:73]
	v_or_b32_e32 v70, s19, v65
	v_lshl_add_u64 v[72:73], v[72:73], 0, s[14:15]
	v_lshlrev_b64 v[70:71], 9, v[70:71]
	v_lshl_add_u64 v[72:73], v[72:73], 0, s[92:93]
	v_lshl_add_u64 v[70:71], s[96:97], 0, v[70:71]
	v_lshl_add_u64 v[72:73], v[72:73], 0, v[128:129]
	v_lshl_add_u64 v[70:71], v[70:71], 0, s[14:15]
	v_cvt_pk_bf16_f32 v238, v78, v79
	v_cvt_pk_bf16_f32 v239, v80, v81
	v_cvt_pk_bf16_f32 v240, v82, v83
	v_cvt_pk_bf16_f32 v241, v84, v85
	v_lshl_add_u64 v[72:73], v[72:73], 0, v[140:141]
	s_nop 0
	v_permlane16_swap_b32_e32 v238, v240
	v_permlane16_swap_b32_e32 v239, v241
	global_store_dwordx4 v[72:73], v[238:241], off
	s_nop 1
	v_lshl_add_u64 v[70:71], v[70:71], 0, s[92:93]
	v_lshl_add_u64 v[70:71], v[70:71], 0, v[128:129]
	v_cvt_pk_bf16_f32 v238, v188, v189
	v_cvt_pk_bf16_f32 v239, v190, v191
	v_cvt_pk_bf16_f32 v240, v192, v193
	v_cvt_pk_bf16_f32 v241, v194, v195
	v_lshl_add_u64 v[70:71], v[70:71], 0, v[140:141]
	s_nop 0
	v_permlane16_swap_b32_e32 v238, v240
	v_permlane16_swap_b32_e32 v239, v241
	global_store_dwordx4 v[70:71], v[238:241], off
	s_nop 1
	v_or_b32_e32 v70, 48, v64
	v_ashrrev_i32_e32 v71, 31, v70
	v_lshlrev_b64 v[70:71], 8, v[70:71]
	v_or_b32_e32 v65, s18, v70
	v_or_b32_e32 v70, s13, v65
	v_lshlrev_b64 v[72:73], 9, v[70:71]
	v_lshl_add_u64 v[72:73], s[96:97], 0, v[72:73]
	v_lshl_add_u64 v[72:73], v[72:73], 0, s[14:15]
	v_lshl_add_u64 v[72:73], v[72:73], 0, s[92:93]
	v_lshl_add_u64 v[72:73], v[72:73], 0, v[128:129]
	v_or_b32_e32 v70, s19, v65
	v_cvt_pk_bf16_f32 v238, v52, v53
	v_cvt_pk_bf16_f32 v239, v54, v55
	v_cvt_pk_bf16_f32 v240, v48, v49
	v_cvt_pk_bf16_f32 v241, v50, v51
	v_lshl_add_u64 v[72:73], v[72:73], 0, v[140:141]
	s_nop 0
	v_permlane16_swap_b32_e32 v238, v240
	v_permlane16_swap_b32_e32 v239, v241
	global_store_dwordx4 v[72:73], v[238:241], off
	s_nop 1
	v_lshlrev_b64 v[48:49], 9, v[70:71]
	v_lshl_add_u64 v[48:49], s[96:97], 0, v[48:49]
	v_lshl_add_u64 v[48:49], v[48:49], 0, s[14:15]
	v_lshl_add_u64 v[48:49], v[48:49], 0, s[92:93]
	v_lshl_add_u64 v[48:49], v[48:49], 0, v[128:129]
	v_cvt_pk_bf16_f32 v238, v196, v197
	v_cvt_pk_bf16_f32 v239, v198, v199
	v_cvt_pk_bf16_f32 v240, v200, v201
	v_cvt_pk_bf16_f32 v241, v202, v203
	v_lshl_add_u64 v[48:49], v[48:49], 0, v[140:141]
	s_nop 0
	v_permlane16_swap_b32_e32 v238, v240
	v_permlane16_swap_b32_e32 v239, v241
	global_store_dwordx4 v[48:49], v[238:241], off
	s_nop 1
	v_add_u32_e32 v48, 0x80, v64
	v_ashrrev_i32_e32 v49, 31, v48
	v_lshlrev_b64 v[48:49], 8, v[48:49]
	v_or_b32_e32 v54, s18, v48
	v_or_b32_e32 v48, s13, v54
	v_lshlrev_b64 v[50:51], 9, v[48:49]
	v_lshl_add_u64 v[50:51], s[96:97], 0, v[50:51]
	v_or_b32_e32 v48, s19, v54
	v_lshl_add_u64 v[50:51], v[50:51], 0, s[14:15]
	v_lshlrev_b64 v[48:49], 9, v[48:49]
	v_lshl_add_u64 v[50:51], v[50:51], 0, s[92:93]
	v_lshl_add_u64 v[48:49], s[96:97], 0, v[48:49]
	v_lshl_add_u64 v[50:51], v[50:51], 0, v[128:129]
	v_lshl_add_u64 v[48:49], v[48:49], 0, s[14:15]
	v_cvt_pk_bf16_f32 v238, v160, v161
	v_cvt_pk_bf16_f32 v239, v162, v163
	v_cvt_pk_bf16_f32 v240, v164, v165
	v_cvt_pk_bf16_f32 v241, v166, v167
	v_lshl_add_u64 v[50:51], v[50:51], 0, v[140:141]
	s_nop 0
	v_permlane16_swap_b32_e32 v238, v240
	v_permlane16_swap_b32_e32 v239, v241
	global_store_dwordx4 v[50:51], v[238:241], off
	s_nop 1
	v_lshl_add_u64 v[48:49], v[48:49], 0, s[92:93]
	v_lshl_add_u64 v[48:49], v[48:49], 0, v[128:129]
	v_cvt_pk_bf16_f32 v238, v118, v119
	v_cvt_pk_bf16_f32 v239, v120, v121
	v_cvt_pk_bf16_f32 v240, v122, v123
	v_cvt_pk_bf16_f32 v241, v124, v125
	v_lshl_add_u64 v[48:49], v[48:49], 0, v[140:141]
	s_nop 0
	v_permlane16_swap_b32_e32 v238, v240
	v_permlane16_swap_b32_e32 v239, v241
	global_store_dwordx4 v[48:49], v[238:241], off
	s_nop 1
	v_add_u32_e32 v48, 0x90, v64
	v_ashrrev_i32_e32 v49, 31, v48
	v_lshlrev_b64 v[48:49], 8, v[48:49]
	v_or_b32_e32 v52, s18, v48
	v_or_b32_e32 v48, s13, v52
	v_lshlrev_b64 v[50:51], 9, v[48:49]
	v_lshl_add_u64 v[50:51], s[96:97], 0, v[50:51]
	v_lshl_add_u64 v[50:51], v[50:51], 0, s[14:15]
	v_lshl_add_u64 v[50:51], v[50:51], 0, s[92:93]
	v_lshl_add_u64 v[50:51], v[50:51], 0, v[128:129]
	v_or_b32_e32 v48, s19, v52
	v_cvt_pk_bf16_f32 v238, v36, v37
	v_cvt_pk_bf16_f32 v239, v38, v39
	v_cvt_pk_bf16_f32 v240, v32, v33
	v_cvt_pk_bf16_f32 v241, v34, v35
	v_lshl_add_u64 v[50:51], v[50:51], 0, v[140:141]
	s_nop 0
	v_permlane16_swap_b32_e32 v238, v240
	v_permlane16_swap_b32_e32 v239, v241
	global_store_dwordx4 v[50:51], v[238:241], off
	s_nop 1
	v_lshlrev_b64 v[32:33], 9, v[48:49]
	v_lshl_add_u64 v[32:33], s[96:97], 0, v[32:33]
	v_lshl_add_u64 v[32:33], v[32:33], 0, s[14:15]
	v_lshl_add_u64 v[32:33], v[32:33], 0, s[92:93]
	v_lshl_add_u64 v[32:33], v[32:33], 0, v[128:129]
	v_cvt_pk_bf16_f32 v238, v44, v45
	v_cvt_pk_bf16_f32 v239, v46, v47
	v_cvt_pk_bf16_f32 v240, v40, v41
	v_cvt_pk_bf16_f32 v241, v42, v43
	v_lshl_add_u64 v[32:33], v[32:33], 0, v[140:141]
	s_nop 0
	v_permlane16_swap_b32_e32 v238, v240
	v_permlane16_swap_b32_e32 v239, v241
	global_store_dwordx4 v[32:33], v[238:241], off
	s_nop 1
	v_add_u32_e32 v32, 0xa0, v64
	v_ashrrev_i32_e32 v33, 31, v32
	v_lshlrev_b64 v[32:33], 8, v[32:33]
	v_or_b32_e32 v36, s18, v32
	v_or_b32_e32 v32, s13, v36
	v_lshlrev_b64 v[34:35], 9, v[32:33]
	v_lshl_add_u64 v[34:35], s[96:97], 0, v[34:35]
	v_lshl_add_u64 v[34:35], v[34:35], 0, s[14:15]
	v_lshl_add_u64 v[34:35], v[34:35], 0, s[92:93]
	v_lshl_add_u64 v[34:35], v[34:35], 0, v[128:129]
	v_or_b32_e32 v32, s19, v36
	v_cvt_pk_bf16_f32 v238, v20, v21
	v_cvt_pk_bf16_f32 v239, v22, v23
	v_cvt_pk_bf16_f32 v240, v16, v17
	v_cvt_pk_bf16_f32 v241, v18, v19
	v_lshl_add_u64 v[34:35], v[34:35], 0, v[140:141]
	s_nop 0
	v_permlane16_swap_b32_e32 v238, v240
	v_permlane16_swap_b32_e32 v239, v241
	global_store_dwordx4 v[34:35], v[238:241], off
	s_nop 1
	v_lshlrev_b64 v[16:17], 9, v[32:33]
	v_lshl_add_u64 v[16:17], s[96:97], 0, v[16:17]
	v_lshl_add_u64 v[16:17], v[16:17], 0, s[14:15]
	v_lshl_add_u64 v[16:17], v[16:17], 0, s[92:93]
	v_lshl_add_u64 v[16:17], v[16:17], 0, v[128:129]
	v_cvt_pk_bf16_f32 v238, v28, v29
	v_cvt_pk_bf16_f32 v239, v30, v31
	v_cvt_pk_bf16_f32 v240, v24, v25
	v_cvt_pk_bf16_f32 v241, v26, v27
	v_lshl_add_u64 v[16:17], v[16:17], 0, v[140:141]
	s_nop 0
	v_permlane16_swap_b32_e32 v238, v240
	v_permlane16_swap_b32_e32 v239, v241
	global_store_dwordx4 v[16:17], v[238:241], off
	s_nop 1
	v_add_u32_e32 v16, 0xb0, v64
	v_ashrrev_i32_e32 v17, 31, v16
	v_lshlrev_b64 v[16:17], 8, v[16:17]
	v_or_b32_e32 v20, s18, v16
	v_or_b32_e32 v16, s13, v20
	v_lshlrev_b64 v[18:19], 9, v[16:17]
	v_lshl_add_u64 v[18:19], s[96:97], 0, v[18:19]
	v_lshl_add_u64 v[18:19], v[18:19], 0, s[14:15]
	v_lshl_add_u64 v[18:19], v[18:19], 0, s[92:93]
	v_lshl_add_u64 v[18:19], v[18:19], 0, v[128:129]
	v_or_b32_e32 v16, s19, v20
	v_cvt_pk_bf16_f32 v238, v4, v5
	v_cvt_pk_bf16_f32 v239, v6, v7
	v_cvt_pk_bf16_f32 v240, v0, v1
	v_cvt_pk_bf16_f32 v241, v2, v3
	v_lshl_add_u64 v[18:19], v[18:19], 0, v[140:141]
	s_nop 0
	v_permlane16_swap_b32_e32 v238, v240
	v_permlane16_swap_b32_e32 v239, v241
	global_store_dwordx4 v[18:19], v[238:241], off
	s_nop 1
	v_lshlrev_b64 v[0:1], 9, v[16:17]
	v_lshl_add_u64 v[0:1], s[96:97], 0, v[0:1]
	v_lshl_add_u64 v[0:1], v[0:1], 0, s[14:15]
	v_lshl_add_u64 v[0:1], v[0:1], 0, s[92:93]
	v_lshl_add_u64 v[0:1], v[0:1], 0, v[128:129]
	v_cvt_pk_bf16_f32 v238, v12, v13
	v_cvt_pk_bf16_f32 v239, v14, v15
	v_cvt_pk_bf16_f32 v240, v8, v9
	v_cvt_pk_bf16_f32 v241, v10, v11
	v_lshl_add_u64 v[0:1], v[0:1], 0, v[140:141]
	s_nop 0
	v_permlane16_swap_b32_e32 v238, v240
	v_permlane16_swap_b32_e32 v239, v241
	global_store_dwordx4 v[0:1], v[238:241], off
	s_nop 1
	s_add_i32 s34, s34, s90
	s_andn2_b64 vcc, exec, s[38:39]
	s_mov_b32 s44, s12
	s_mov_b32 s36, s35
	s_mov_b64 s[18:19], s[30:31]
	s_mov_b64 s[14:15], s[42:43]
	v_readlane_b32 s20, v255, 27
	s_cbranch_vccz .LBB0_113
